# write-through (sc1) for full-line stores in front of releases: gate tiles (their per-workgroup L2 release dropped, as for MERGED), Fourier stage B outputs, phase-0 weight copies
# speedup vs baseline: 1.0112x; 1.0112x over previous
.LBB0_286:
	s_bfe_u32 s0, s56, 0x60002
	s_and_b32 s1, s56, 3
	s_cmp_eq_u32 s0, 1
	s_mov_b32 s4, 0x7900000
	s_cselect_b32 s4, s4, 0x19900000
	s_cmp_lg_u32 s0, 0
	s_cselect_b32 s0, s4, 0x15100000
	v_readlane_b32 s4, v255, 8
	s_add_u32 s4, s4, s0
	v_readlane_b32 s0, v255, 9
	s_addc_u32 s5, s0, 0
	s_lshl_b32 s0, s46, 2
	v_mul_f32_e32 v120, 0xbfb8aa3b, v120
	s_or_b32 s0, s0, s1
	v_mul_f32_e32 v124, 0xbfb8aa3b, v124
	v_exp_f32_e32 v120, v120
	v_mul_f32_e32 v121, 0xbfb8aa3b, v121
	s_ashr_i32 s1, s0, 31
	v_exp_f32_e32 v130, v124
	v_exp_f32_e32 v121, v121
	s_lshl_b64 s[0:1], s[0:1], 17
	v_mov_b32_e32 v128, v221
	s_add_u32 s0, s4, s0
	s_addc_u32 s1, s5, s1
	v_ashrrev_i32_e32 v129, 31, v128
	v_mul_f32_e32 v124, 0xbfb8aa3b, v125
	v_add_f32_e32 v120, 1.0, v120
	v_exp_f32_e32 v131, v124
	v_lshl_add_u64 v[124:125], v[128:129], 4, s[0:1]
	v_add_f32_e32 v128, 1.0, v130
	v_rcp_f32_e32 v130, v120
	v_add_f32_e32 v120, 1.0, v121
	v_mul_f32_e32 v121, 0xbfb8aa3b, v122
	v_mul_f32_e32 v126, 0xbfb8aa3b, v126
	v_mul_f32_e32 v127, 0xbfb8aa3b, v127
	v_exp_f32_e32 v121, v121
	v_mul_f32_e32 v122, 0xbfb8aa3b, v123
	v_exp_f32_e32 v126, v126
	v_exp_f32_e32 v127, v127
	v_exp_f32_e32 v122, v122
	v_rcp_f32_e32 v123, v120
	v_add_f32_e32 v120, 1.0, v121
	v_add_f32_e32 v129, 1.0, v131
	v_add_f32_e32 v126, 1.0, v126
	v_add_f32_e32 v127, 1.0, v127
	v_rcp_f32_e32 v131, v120
	v_add_f32_e32 v120, 1.0, v122
	v_mul_f32_e32 v112, 0xbfb8aa3b, v112
	v_rcp_f32_e32 v128, v128
	v_rcp_f32_e32 v129, v129
	v_rcp_f32_e32 v126, v126
	v_rcp_f32_e32 v127, v127
	v_rcp_f32_e32 v132, v120
	v_exp_f32_e32 v112, v112
	v_mul_f32_e32 v113, 0xbfb8aa3b, v113
	v_exp_f32_e32 v113, v113
	v_cvt_pk_bf16_f32 v120, v128, v129
	v_cvt_pk_bf16_f32 v121, v126, v127
	v_cvt_pk_bf16_f32 v122, v130, v123
	v_cvt_pk_bf16_f32 v123, v131, v132
	v_add_f32_e32 v112, 1.0, v112
	v_mul_f32_e32 v116, 0xbfb8aa3b, v116
	v_mul_f32_e32 v117, 0xbfb8aa3b, v117
	global_store_dwordx4 v[124:125], v[120:123], off sc1
	v_exp_f32_e32 v116, v116
	v_exp_f32_e32 v117, v117
	v_rcp_f32_e32 v120, v112
	v_add_f32_e32 v112, 1.0, v113
	v_mul_f32_e32 v113, 0xbfb8aa3b, v114
	v_mul_f32_e32 v118, 0xbfb8aa3b, v118
	v_mul_f32_e32 v119, 0xbfb8aa3b, v119
	v_exp_f32_e32 v113, v113
	v_mul_f32_e32 v114, 0xbfb8aa3b, v115
	v_exp_f32_e32 v118, v118
	v_exp_f32_e32 v119, v119
	v_exp_f32_e32 v114, v114
	v_add_f32_e32 v116, 1.0, v116
	v_add_f32_e32 v117, 1.0, v117
	v_rcp_f32_e32 v115, v112
	v_add_f32_e32 v112, 1.0, v113
	v_rcp_f32_e32 v116, v116
	v_rcp_f32_e32 v117, v117
	v_add_f32_e32 v118, 1.0, v118
	v_add_f32_e32 v119, 1.0, v119
	v_rcp_f32_e32 v121, v112
	v_add_f32_e32 v112, 1.0, v114
	v_mul_f32_e32 v104, 0xbfb8aa3b, v104
	v_rcp_f32_e32 v118, v118
	v_rcp_f32_e32 v119, v119
	v_rcp_f32_e32 v122, v112
	v_exp_f32_e32 v104, v104
	v_mul_f32_e32 v105, 0xbfb8aa3b, v105
	v_exp_f32_e32 v105, v105
	s_movk_i32 s0, 0x2000
	v_cvt_pk_bf16_f32 v112, v116, v117
	v_add_co_u32_e32 v116, vcc, s0, v124
	v_cvt_pk_bf16_f32 v113, v118, v119
	v_cvt_pk_bf16_f32 v114, v120, v115
	v_cvt_pk_bf16_f32 v115, v121, v122
	v_addc_co_u32_e32 v117, vcc, 0, v125, vcc
	v_add_f32_e32 v104, 1.0, v104
	v_mul_f32_e32 v108, 0xbfb8aa3b, v108
	v_mul_f32_e32 v109, 0xbfb8aa3b, v109
	global_store_dwordx4 v[116:117], v[112:115], off sc1
	v_exp_f32_e32 v108, v108
	v_exp_f32_e32 v109, v109
	v_rcp_f32_e32 v112, v104
	v_add_f32_e32 v104, 1.0, v105
	v_mul_f32_e32 v105, 0xbfb8aa3b, v106
	v_mul_f32_e32 v110, 0xbfb8aa3b, v110
	v_mul_f32_e32 v111, 0xbfb8aa3b, v111
	v_exp_f32_e32 v105, v105
	v_mul_f32_e32 v106, 0xbfb8aa3b, v107
	v_exp_f32_e32 v110, v110
	v_exp_f32_e32 v111, v111
	v_exp_f32_e32 v106, v106
	v_add_f32_e32 v108, 1.0, v108
	v_add_f32_e32 v109, 1.0, v109
	v_rcp_f32_e32 v107, v104
	v_add_f32_e32 v104, 1.0, v105
	v_rcp_f32_e32 v108, v108
	v_rcp_f32_e32 v109, v109
	v_add_f32_e32 v110, 1.0, v110
	v_add_f32_e32 v111, 1.0, v111
	v_rcp_f32_e32 v113, v104
	v_add_f32_e32 v104, 1.0, v106
	v_mul_f32_e32 v96, 0xbfb8aa3b, v96
	v_rcp_f32_e32 v110, v110
	v_rcp_f32_e32 v111, v111
	v_rcp_f32_e32 v114, v104
	v_exp_f32_e32 v96, v96
	v_mul_f32_e32 v97, 0xbfb8aa3b, v97
	v_exp_f32_e32 v97, v97
	s_movk_i32 s0, 0x4000
	v_cvt_pk_bf16_f32 v104, v108, v109
	v_add_co_u32_e32 v108, vcc, s0, v124
	v_cvt_pk_bf16_f32 v105, v110, v111
	v_cvt_pk_bf16_f32 v106, v112, v107
	v_cvt_pk_bf16_f32 v107, v113, v114
	v_addc_co_u32_e32 v109, vcc, 0, v125, vcc
	v_add_f32_e32 v96, 1.0, v96
	v_mul_f32_e32 v100, 0xbfb8aa3b, v100
	v_mul_f32_e32 v101, 0xbfb8aa3b, v101
	global_store_dwordx4 v[108:109], v[104:107], off sc1
	v_exp_f32_e32 v100, v100
	v_exp_f32_e32 v101, v101
	v_rcp_f32_e32 v104, v96
	v_add_f32_e32 v96, 1.0, v97
	v_mul_f32_e32 v97, 0xbfb8aa3b, v98
	v_mul_f32_e32 v102, 0xbfb8aa3b, v102
	v_mul_f32_e32 v103, 0xbfb8aa3b, v103
	v_exp_f32_e32 v97, v97
	v_mul_f32_e32 v98, 0xbfb8aa3b, v99
	v_exp_f32_e32 v102, v102
	v_exp_f32_e32 v103, v103
	v_exp_f32_e32 v98, v98
	v_add_f32_e32 v100, 1.0, v100
	v_add_f32_e32 v101, 1.0, v101
	v_rcp_f32_e32 v99, v96
	v_add_f32_e32 v96, 1.0, v97
	v_rcp_f32_e32 v100, v100
	v_rcp_f32_e32 v101, v101
	v_add_f32_e32 v102, 1.0, v102
	v_add_f32_e32 v103, 1.0, v103
	v_rcp_f32_e32 v105, v96
	v_add_f32_e32 v96, 1.0, v98
	v_mul_f32_e32 v88, 0xbfb8aa3b, v88
	v_rcp_f32_e32 v102, v102
	v_rcp_f32_e32 v103, v103
	v_rcp_f32_e32 v106, v96
	v_exp_f32_e32 v88, v88
	v_mul_f32_e32 v89, 0xbfb8aa3b, v89
	v_exp_f32_e32 v89, v89
	s_movk_i32 s0, 0x6000
	v_cvt_pk_bf16_f32 v96, v100, v101
	v_add_co_u32_e32 v100, vcc, s0, v124
	v_cvt_pk_bf16_f32 v97, v102, v103
	v_cvt_pk_bf16_f32 v98, v104, v99
	v_cvt_pk_bf16_f32 v99, v105, v106
	v_addc_co_u32_e32 v101, vcc, 0, v125, vcc
	v_add_f32_e32 v88, 1.0, v88
	v_mul_f32_e32 v92, 0xbfb8aa3b, v92
	v_mul_f32_e32 v93, 0xbfb8aa3b, v93
	global_store_dwordx4 v[100:101], v[96:99], off sc1
	v_exp_f32_e32 v92, v92
	v_exp_f32_e32 v93, v93
	v_rcp_f32_e32 v96, v88
	v_add_f32_e32 v88, 1.0, v89
	v_mul_f32_e32 v89, 0xbfb8aa3b, v90
	v_mul_f32_e32 v94, 0xbfb8aa3b, v94
	v_mul_f32_e32 v95, 0xbfb8aa3b, v95
	v_exp_f32_e32 v89, v89
	v_mul_f32_e32 v90, 0xbfb8aa3b, v91
	v_exp_f32_e32 v94, v94
	v_exp_f32_e32 v95, v95
	v_exp_f32_e32 v90, v90
	v_add_f32_e32 v92, 1.0, v92
	v_add_f32_e32 v93, 1.0, v93
	v_rcp_f32_e32 v91, v88
	v_add_f32_e32 v88, 1.0, v89
	v_rcp_f32_e32 v92, v92
	v_rcp_f32_e32 v93, v93
	v_add_f32_e32 v94, 1.0, v94
	v_add_f32_e32 v95, 1.0, v95
	v_rcp_f32_e32 v97, v88
	v_add_f32_e32 v88, 1.0, v90
	v_mul_f32_e32 v80, 0xbfb8aa3b, v80
	v_rcp_f32_e32 v94, v94
	v_rcp_f32_e32 v95, v95
	v_rcp_f32_e32 v98, v88
	v_exp_f32_e32 v80, v80
	v_mul_f32_e32 v81, 0xbfb8aa3b, v81
	v_exp_f32_e32 v81, v81
	s_mov_b32 s0, 0x8000
	v_cvt_pk_bf16_f32 v88, v92, v93
	v_add_co_u32_e32 v92, vcc, s0, v124
	v_cvt_pk_bf16_f32 v89, v94, v95
	v_cvt_pk_bf16_f32 v90, v96, v91
	v_cvt_pk_bf16_f32 v91, v97, v98
	v_addc_co_u32_e32 v93, vcc, 0, v125, vcc
	v_add_f32_e32 v80, 1.0, v80
	v_mul_f32_e32 v84, 0xbfb8aa3b, v84
	v_mul_f32_e32 v85, 0xbfb8aa3b, v85
	global_store_dwordx4 v[92:93], v[88:91], off sc1
	v_exp_f32_e32 v84, v84
	v_exp_f32_e32 v85, v85
	v_rcp_f32_e32 v88, v80
	v_add_f32_e32 v80, 1.0, v81
	v_mul_f32_e32 v81, 0xbfb8aa3b, v82
	v_mul_f32_e32 v86, 0xbfb8aa3b, v86
	v_mul_f32_e32 v87, 0xbfb8aa3b, v87
	v_exp_f32_e32 v81, v81
	v_mul_f32_e32 v82, 0xbfb8aa3b, v83
	v_exp_f32_e32 v86, v86
	v_exp_f32_e32 v87, v87
	v_exp_f32_e32 v82, v82
	v_add_f32_e32 v84, 1.0, v84
	v_add_f32_e32 v85, 1.0, v85
	v_rcp_f32_e32 v83, v80
	v_add_f32_e32 v80, 1.0, v81
	v_rcp_f32_e32 v84, v84
	v_rcp_f32_e32 v85, v85
	v_add_f32_e32 v86, 1.0, v86
	v_add_f32_e32 v87, 1.0, v87
	v_rcp_f32_e32 v89, v80
	v_add_f32_e32 v80, 1.0, v82
	v_mul_f32_e32 v72, 0xbfb8aa3b, v72
	v_rcp_f32_e32 v86, v86
	v_rcp_f32_e32 v87, v87
	v_rcp_f32_e32 v90, v80
	v_exp_f32_e32 v72, v72
	v_mul_f32_e32 v73, 0xbfb8aa3b, v73
	v_exp_f32_e32 v73, v73
	s_mov_b32 s0, 0xa000
	v_cvt_pk_bf16_f32 v80, v84, v85
	v_add_co_u32_e32 v84, vcc, s0, v124
	v_cvt_pk_bf16_f32 v81, v86, v87
	v_cvt_pk_bf16_f32 v82, v88, v83
	v_cvt_pk_bf16_f32 v83, v89, v90
	v_addc_co_u32_e32 v85, vcc, 0, v125, vcc
	v_add_f32_e32 v72, 1.0, v72
	v_mul_f32_e32 v76, 0xbfb8aa3b, v76
	v_mul_f32_e32 v77, 0xbfb8aa3b, v77
	global_store_dwordx4 v[84:85], v[80:83], off sc1
	v_exp_f32_e32 v76, v76
	v_exp_f32_e32 v77, v77
	v_rcp_f32_e32 v80, v72
	v_add_f32_e32 v72, 1.0, v73
	v_mul_f32_e32 v73, 0xbfb8aa3b, v74
	v_mul_f32_e32 v78, 0xbfb8aa3b, v78
	v_mul_f32_e32 v79, 0xbfb8aa3b, v79
	v_exp_f32_e32 v73, v73
	v_mul_f32_e32 v74, 0xbfb8aa3b, v75
	v_exp_f32_e32 v78, v78
	v_exp_f32_e32 v79, v79
	v_exp_f32_e32 v74, v74
	v_add_f32_e32 v76, 1.0, v76
	v_add_f32_e32 v77, 1.0, v77
	v_rcp_f32_e32 v75, v72
	v_add_f32_e32 v72, 1.0, v73
	v_rcp_f32_e32 v76, v76
	v_rcp_f32_e32 v77, v77
	v_add_f32_e32 v78, 1.0, v78
	v_add_f32_e32 v79, 1.0, v79
	v_rcp_f32_e32 v81, v72
	v_add_f32_e32 v72, 1.0, v74
	v_mul_f32_e32 v64, 0xbfb8aa3b, v64
	v_rcp_f32_e32 v78, v78
	v_rcp_f32_e32 v79, v79
	v_rcp_f32_e32 v82, v72
	v_exp_f32_e32 v64, v64
	v_mul_f32_e32 v65, 0xbfb8aa3b, v65
	v_exp_f32_e32 v65, v65
	s_mov_b32 s0, 0xc000
	v_cvt_pk_bf16_f32 v72, v76, v77
	v_add_co_u32_e32 v76, vcc, s0, v124
	v_cvt_pk_bf16_f32 v73, v78, v79
	v_cvt_pk_bf16_f32 v74, v80, v75
	v_cvt_pk_bf16_f32 v75, v81, v82
	v_addc_co_u32_e32 v77, vcc, 0, v125, vcc
	v_add_f32_e32 v64, 1.0, v64
	v_mul_f32_e32 v68, 0xbfb8aa3b, v68
	v_mul_f32_e32 v69, 0xbfb8aa3b, v69
	global_store_dwordx4 v[76:77], v[72:75], off sc1
	v_exp_f32_e32 v68, v68
	v_exp_f32_e32 v69, v69
	v_rcp_f32_e32 v72, v64
	v_add_f32_e32 v64, 1.0, v65
	v_mul_f32_e32 v65, 0xbfb8aa3b, v66
	v_mul_f32_e32 v70, 0xbfb8aa3b, v70
	v_mul_f32_e32 v71, 0xbfb8aa3b, v71
	v_exp_f32_e32 v65, v65
	v_mul_f32_e32 v66, 0xbfb8aa3b, v67
	v_exp_f32_e32 v70, v70
	v_exp_f32_e32 v71, v71
	v_exp_f32_e32 v66, v66
	v_add_f32_e32 v68, 1.0, v68
	v_add_f32_e32 v69, 1.0, v69
	v_rcp_f32_e32 v67, v64
	v_add_f32_e32 v64, 1.0, v65
	v_rcp_f32_e32 v68, v68
	v_rcp_f32_e32 v69, v69
	v_add_f32_e32 v70, 1.0, v70
	v_add_f32_e32 v71, 1.0, v71
	v_rcp_f32_e32 v73, v64
	v_add_f32_e32 v64, 1.0, v66
	v_mul_f32_e32 v56, 0xbfb8aa3b, v56
	v_rcp_f32_e32 v70, v70
	v_rcp_f32_e32 v71, v71
	v_rcp_f32_e32 v74, v64
	v_exp_f32_e32 v56, v56
	v_mul_f32_e32 v57, 0xbfb8aa3b, v57
	v_exp_f32_e32 v57, v57
	s_mov_b32 s0, 0xe000
	v_cvt_pk_bf16_f32 v64, v68, v69
	v_add_co_u32_e32 v68, vcc, s0, v124
	v_cvt_pk_bf16_f32 v65, v70, v71
	v_cvt_pk_bf16_f32 v66, v72, v67
	v_cvt_pk_bf16_f32 v67, v73, v74
	v_addc_co_u32_e32 v69, vcc, 0, v125, vcc
	v_add_f32_e32 v56, 1.0, v56
	v_mul_f32_e32 v60, 0xbfb8aa3b, v60
	v_mul_f32_e32 v61, 0xbfb8aa3b, v61
	global_store_dwordx4 v[68:69], v[64:67], off sc1
	v_exp_f32_e32 v60, v60
	v_exp_f32_e32 v61, v61
	v_rcp_f32_e32 v64, v56
	v_add_f32_e32 v56, 1.0, v57
	v_mul_f32_e32 v57, 0xbfb8aa3b, v58
	v_mul_f32_e32 v62, 0xbfb8aa3b, v62
	v_mul_f32_e32 v63, 0xbfb8aa3b, v63
	v_exp_f32_e32 v57, v57
	v_mul_f32_e32 v58, 0xbfb8aa3b, v59
	v_exp_f32_e32 v62, v62
	v_exp_f32_e32 v63, v63
	v_exp_f32_e32 v58, v58
	v_add_f32_e32 v60, 1.0, v60
	v_add_f32_e32 v61, 1.0, v61
	v_rcp_f32_e32 v59, v56
	v_add_f32_e32 v56, 1.0, v57
	v_rcp_f32_e32 v60, v60
	v_rcp_f32_e32 v61, v61
	v_add_f32_e32 v62, 1.0, v62
	v_add_f32_e32 v63, 1.0, v63
	v_rcp_f32_e32 v65, v56
	v_add_f32_e32 v56, 1.0, v58
	v_mul_f32_e32 v48, 0xbfb8aa3b, v48
	v_rcp_f32_e32 v62, v62
	v_rcp_f32_e32 v63, v63
	v_rcp_f32_e32 v66, v56
	v_exp_f32_e32 v48, v48
	v_mul_f32_e32 v49, 0xbfb8aa3b, v49
	v_exp_f32_e32 v49, v49
	s_mov_b32 s0, 0x10000
	v_cvt_pk_bf16_f32 v56, v60, v61
	v_add_co_u32_e32 v60, vcc, s0, v124
	v_cvt_pk_bf16_f32 v57, v62, v63
	v_cvt_pk_bf16_f32 v58, v64, v59
	v_cvt_pk_bf16_f32 v59, v65, v66
	v_addc_co_u32_e32 v61, vcc, 0, v125, vcc
	v_add_f32_e32 v48, 1.0, v48
	v_mul_f32_e32 v52, 0xbfb8aa3b, v52
	v_mul_f32_e32 v53, 0xbfb8aa3b, v53
	global_store_dwordx4 v[60:61], v[56:59], off sc1
	v_exp_f32_e32 v52, v52
	v_exp_f32_e32 v53, v53
	v_rcp_f32_e32 v56, v48
	v_add_f32_e32 v48, 1.0, v49
	v_mul_f32_e32 v49, 0xbfb8aa3b, v50
	v_mul_f32_e32 v54, 0xbfb8aa3b, v54
	v_mul_f32_e32 v55, 0xbfb8aa3b, v55
	v_exp_f32_e32 v49, v49
	v_mul_f32_e32 v50, 0xbfb8aa3b, v51
	v_exp_f32_e32 v54, v54
	v_exp_f32_e32 v55, v55
	v_exp_f32_e32 v50, v50
	v_add_f32_e32 v52, 1.0, v52
	v_add_f32_e32 v53, 1.0, v53
	v_rcp_f32_e32 v51, v48
	v_add_f32_e32 v48, 1.0, v49
	v_rcp_f32_e32 v52, v52
	v_rcp_f32_e32 v53, v53
	v_add_f32_e32 v54, 1.0, v54
	v_add_f32_e32 v55, 1.0, v55
	v_rcp_f32_e32 v57, v48
	v_add_f32_e32 v48, 1.0, v50
	v_mul_f32_e32 v40, 0xbfb8aa3b, v40
	v_rcp_f32_e32 v54, v54
	v_rcp_f32_e32 v55, v55
	v_rcp_f32_e32 v58, v48
	v_exp_f32_e32 v40, v40
	v_mul_f32_e32 v41, 0xbfb8aa3b, v41
	v_exp_f32_e32 v41, v41
	s_mov_b32 s0, 0x12000
	v_cvt_pk_bf16_f32 v48, v52, v53
	v_add_co_u32_e32 v52, vcc, s0, v124
	v_cvt_pk_bf16_f32 v49, v54, v55
	v_cvt_pk_bf16_f32 v50, v56, v51
	v_cvt_pk_bf16_f32 v51, v57, v58
	v_addc_co_u32_e32 v53, vcc, 0, v125, vcc
	v_add_f32_e32 v40, 1.0, v40
	v_mul_f32_e32 v44, 0xbfb8aa3b, v44
	v_mul_f32_e32 v45, 0xbfb8aa3b, v45
	global_store_dwordx4 v[52:53], v[48:51], off sc1
	v_exp_f32_e32 v44, v44
	v_exp_f32_e32 v45, v45
	v_rcp_f32_e32 v48, v40
	v_add_f32_e32 v40, 1.0, v41
	v_mul_f32_e32 v41, 0xbfb8aa3b, v42
	v_mul_f32_e32 v46, 0xbfb8aa3b, v46
	v_mul_f32_e32 v47, 0xbfb8aa3b, v47
	v_exp_f32_e32 v41, v41
	v_mul_f32_e32 v42, 0xbfb8aa3b, v43
	v_exp_f32_e32 v46, v46
	v_exp_f32_e32 v47, v47
	v_exp_f32_e32 v42, v42
	v_add_f32_e32 v44, 1.0, v44
	v_add_f32_e32 v45, 1.0, v45
	v_rcp_f32_e32 v43, v40
	v_add_f32_e32 v40, 1.0, v41
	v_rcp_f32_e32 v44, v44
	v_rcp_f32_e32 v45, v45
	v_add_f32_e32 v46, 1.0, v46
	v_add_f32_e32 v47, 1.0, v47
	v_rcp_f32_e32 v49, v40
	v_add_f32_e32 v40, 1.0, v42
	v_mul_f32_e32 v32, 0xbfb8aa3b, v32
	v_rcp_f32_e32 v46, v46
	v_rcp_f32_e32 v47, v47
	v_rcp_f32_e32 v50, v40
	v_exp_f32_e32 v32, v32
	v_mul_f32_e32 v33, 0xbfb8aa3b, v33
	v_exp_f32_e32 v33, v33
	s_mov_b32 s0, 0x14000
	v_cvt_pk_bf16_f32 v40, v44, v45
	v_add_co_u32_e32 v44, vcc, s0, v124
	v_cvt_pk_bf16_f32 v41, v46, v47
	v_cvt_pk_bf16_f32 v42, v48, v43
	v_cvt_pk_bf16_f32 v43, v49, v50
	v_addc_co_u32_e32 v45, vcc, 0, v125, vcc
	v_add_f32_e32 v32, 1.0, v32
	v_mul_f32_e32 v36, 0xbfb8aa3b, v36
	v_mul_f32_e32 v37, 0xbfb8aa3b, v37
	global_store_dwordx4 v[44:45], v[40:43], off sc1
	v_exp_f32_e32 v36, v36
	v_exp_f32_e32 v37, v37
	v_rcp_f32_e32 v40, v32
	v_add_f32_e32 v32, 1.0, v33
	v_mul_f32_e32 v33, 0xbfb8aa3b, v34
	v_mul_f32_e32 v38, 0xbfb8aa3b, v38
	v_mul_f32_e32 v39, 0xbfb8aa3b, v39
	v_exp_f32_e32 v33, v33
	v_mul_f32_e32 v34, 0xbfb8aa3b, v35
	v_exp_f32_e32 v38, v38
	v_exp_f32_e32 v39, v39
	v_exp_f32_e32 v34, v34
	v_add_f32_e32 v36, 1.0, v36
	v_add_f32_e32 v37, 1.0, v37
	v_rcp_f32_e32 v35, v32
	v_add_f32_e32 v32, 1.0, v33
	v_rcp_f32_e32 v36, v36
	v_rcp_f32_e32 v37, v37
	v_add_f32_e32 v38, 1.0, v38
	v_add_f32_e32 v39, 1.0, v39
	v_rcp_f32_e32 v41, v32
	v_add_f32_e32 v32, 1.0, v34
	v_mul_f32_e32 v24, 0xbfb8aa3b, v24
	v_rcp_f32_e32 v38, v38
	v_rcp_f32_e32 v39, v39
	v_rcp_f32_e32 v42, v32
	v_exp_f32_e32 v24, v24
	v_mul_f32_e32 v25, 0xbfb8aa3b, v25
	v_exp_f32_e32 v25, v25
	s_mov_b32 s0, 0x16000
	v_cvt_pk_bf16_f32 v32, v36, v37
	v_add_co_u32_e32 v36, vcc, s0, v124
	v_cvt_pk_bf16_f32 v33, v38, v39
	v_cvt_pk_bf16_f32 v34, v40, v35
	v_cvt_pk_bf16_f32 v35, v41, v42
	v_addc_co_u32_e32 v37, vcc, 0, v125, vcc
	v_add_f32_e32 v24, 1.0, v24
	v_mul_f32_e32 v28, 0xbfb8aa3b, v28
	v_mul_f32_e32 v29, 0xbfb8aa3b, v29
	global_store_dwordx4 v[36:37], v[32:35], off sc1
	v_exp_f32_e32 v28, v28
	v_exp_f32_e32 v29, v29
	v_rcp_f32_e32 v32, v24
	v_add_f32_e32 v24, 1.0, v25
	v_mul_f32_e32 v25, 0xbfb8aa3b, v26
	v_mul_f32_e32 v30, 0xbfb8aa3b, v30
	v_mul_f32_e32 v31, 0xbfb8aa3b, v31
	v_exp_f32_e32 v25, v25
	v_mul_f32_e32 v26, 0xbfb8aa3b, v27
	v_exp_f32_e32 v30, v30
	v_exp_f32_e32 v31, v31
	v_exp_f32_e32 v26, v26
	v_add_f32_e32 v28, 1.0, v28
	v_add_f32_e32 v29, 1.0, v29
	v_rcp_f32_e32 v27, v24
	v_add_f32_e32 v24, 1.0, v25
	v_rcp_f32_e32 v28, v28
	v_rcp_f32_e32 v29, v29
	v_add_f32_e32 v30, 1.0, v30
	v_add_f32_e32 v31, 1.0, v31
	v_rcp_f32_e32 v33, v24
	v_add_f32_e32 v24, 1.0, v26
	v_mul_f32_e32 v16, 0xbfb8aa3b, v16
	v_rcp_f32_e32 v30, v30
	v_rcp_f32_e32 v31, v31
	v_rcp_f32_e32 v34, v24
	v_exp_f32_e32 v16, v16
	v_mul_f32_e32 v17, 0xbfb8aa3b, v17
	v_exp_f32_e32 v17, v17
	v_cvt_pk_bf16_f32 v24, v28, v29
	v_add_co_u32_e32 v28, vcc, s16, v124
	v_cvt_pk_bf16_f32 v25, v30, v31
	v_cvt_pk_bf16_f32 v26, v32, v27
	v_cvt_pk_bf16_f32 v27, v33, v34
	v_addc_co_u32_e32 v29, vcc, 0, v125, vcc
	v_add_f32_e32 v16, 1.0, v16
	v_mul_f32_e32 v20, 0xbfb8aa3b, v20
	v_mul_f32_e32 v21, 0xbfb8aa3b, v21
	global_store_dwordx4 v[28:29], v[24:27], off sc1
	v_exp_f32_e32 v20, v20
	v_exp_f32_e32 v21, v21
	v_rcp_f32_e32 v24, v16
	v_add_f32_e32 v16, 1.0, v17
	v_mul_f32_e32 v17, 0xbfb8aa3b, v18
	v_mul_f32_e32 v22, 0xbfb8aa3b, v22
	v_mul_f32_e32 v23, 0xbfb8aa3b, v23
	v_exp_f32_e32 v17, v17
	v_mul_f32_e32 v18, 0xbfb8aa3b, v19
	v_exp_f32_e32 v22, v22
	v_exp_f32_e32 v23, v23
	v_exp_f32_e32 v18, v18
	v_add_f32_e32 v20, 1.0, v20
	v_add_f32_e32 v21, 1.0, v21
	v_rcp_f32_e32 v19, v16
	v_add_f32_e32 v16, 1.0, v17
	v_rcp_f32_e32 v20, v20
	v_rcp_f32_e32 v21, v21
	v_add_f32_e32 v22, 1.0, v22
	v_add_f32_e32 v23, 1.0, v23
	v_rcp_f32_e32 v25, v16
	v_add_f32_e32 v16, 1.0, v18
	v_mul_f32_e32 v8, 0xbfb8aa3b, v8
	v_rcp_f32_e32 v22, v22
	v_rcp_f32_e32 v23, v23
	v_rcp_f32_e32 v26, v16
	v_exp_f32_e32 v8, v8
	v_mul_f32_e32 v9, 0xbfb8aa3b, v9
	v_exp_f32_e32 v9, v9
	s_mov_b32 s0, 0x1a000
	v_cvt_pk_bf16_f32 v16, v20, v21
	v_add_co_u32_e32 v20, vcc, s0, v124
	v_cvt_pk_bf16_f32 v17, v22, v23
	v_cvt_pk_bf16_f32 v18, v24, v19
	v_cvt_pk_bf16_f32 v19, v25, v26
	v_addc_co_u32_e32 v21, vcc, 0, v125, vcc
	v_add_f32_e32 v8, 1.0, v8
	v_mul_f32_e32 v12, 0xbfb8aa3b, v12
	v_mul_f32_e32 v13, 0xbfb8aa3b, v13
	global_store_dwordx4 v[20:21], v[16:19], off sc1
	v_exp_f32_e32 v12, v12
	v_exp_f32_e32 v13, v13
	v_rcp_f32_e32 v16, v8
	v_add_f32_e32 v8, 1.0, v9
	v_mul_f32_e32 v9, 0xbfb8aa3b, v10
	v_mul_f32_e32 v14, 0xbfb8aa3b, v14
	v_mul_f32_e32 v15, 0xbfb8aa3b, v15
	v_exp_f32_e32 v9, v9
	v_mul_f32_e32 v10, 0xbfb8aa3b, v11
	v_exp_f32_e32 v14, v14
	v_exp_f32_e32 v15, v15
	v_exp_f32_e32 v10, v10
	v_add_f32_e32 v12, 1.0, v12
	v_add_f32_e32 v13, 1.0, v13
	v_rcp_f32_e32 v11, v8
	v_add_f32_e32 v8, 1.0, v9
	v_rcp_f32_e32 v12, v12
	v_rcp_f32_e32 v13, v13
	v_add_f32_e32 v14, 1.0, v14
	v_add_f32_e32 v15, 1.0, v15
	v_rcp_f32_e32 v17, v8
	v_add_f32_e32 v8, 1.0, v10
	v_mul_f32_e32 v0, 0xbfb8aa3b, v0
	v_rcp_f32_e32 v14, v14
	v_rcp_f32_e32 v15, v15
	v_rcp_f32_e32 v18, v8
	v_exp_f32_e32 v0, v0
	v_mul_f32_e32 v1, 0xbfb8aa3b, v1
	v_exp_f32_e32 v1, v1
	s_mov_b32 s0, 0x1c000
	v_cvt_pk_bf16_f32 v8, v12, v13
	v_add_co_u32_e32 v12, vcc, s0, v124
	v_cvt_pk_bf16_f32 v9, v14, v15
	v_cvt_pk_bf16_f32 v10, v16, v11
	v_cvt_pk_bf16_f32 v11, v17, v18
	v_addc_co_u32_e32 v13, vcc, 0, v125, vcc
	v_add_f32_e32 v0, 1.0, v0
	v_mul_f32_e32 v4, 0xbfb8aa3b, v4
	v_mul_f32_e32 v5, 0xbfb8aa3b, v5
	global_store_dwordx4 v[12:13], v[8:11], off sc1
	v_exp_f32_e32 v4, v4
	v_exp_f32_e32 v5, v5
	v_rcp_f32_e32 v8, v0
	v_add_f32_e32 v0, 1.0, v1
	v_mul_f32_e32 v1, 0xbfb8aa3b, v2
	v_mul_f32_e32 v6, 0xbfb8aa3b, v6
	v_mul_f32_e32 v7, 0xbfb8aa3b, v7
	v_exp_f32_e32 v1, v1
	v_mul_f32_e32 v2, 0xbfb8aa3b, v3
	v_exp_f32_e32 v6, v6
	v_exp_f32_e32 v7, v7
	v_exp_f32_e32 v2, v2
	v_add_f32_e32 v4, 1.0, v4
	v_add_f32_e32 v5, 1.0, v5
	v_rcp_f32_e32 v3, v0
	v_add_f32_e32 v0, 1.0, v1
	v_rcp_f32_e32 v4, v4
	v_rcp_f32_e32 v5, v5
	v_add_f32_e32 v6, 1.0, v6
	v_add_f32_e32 v7, 1.0, v7
	v_rcp_f32_e32 v9, v0
	v_add_f32_e32 v0, 1.0, v2
	v_rcp_f32_e32 v6, v6
	v_rcp_f32_e32 v7, v7
	v_rcp_f32_e32 v10, v0
	v_cvt_pk_bf16_f32 v0, v4, v5
	v_add_co_u32_e32 v4, vcc, 0x1e000, v124
	v_cvt_pk_bf16_f32 v1, v6, v7
	v_cvt_pk_bf16_f32 v2, v8, v3
	v_cvt_pk_bf16_f32 v3, v9, v10
	v_addc_co_u32_e32 v5, vcc, 0, v125, vcc
	s_bitcmp0_b32 s56, 8
	global_store_dwordx4 v[4:5], v[0:3], off sc1
	s_cbranch_scc1 .LBB0_305
	s_waitcnt vmcnt(0)
	v_readlane_b32 s4, v254, 51
	v_readlane_b32 s5, v254, 52
	s_barrier
	s_and_saveexec_b64 s[0:1], s[4:5]
	v_readlane_b32 s47, v255, 37
	v_readlane_b32 s51, v255, 38
	s_cbranch_execz .LBB0_304
	s_waitcnt vmcnt(0)
	s_waitcnt vmcnt(0)
	v_readlane_b32 s4, v252, 2
	v_readlane_b32 s5, v252, 3
	s_and_b64 exec, exec, s[4:5]
	s_cbranch_execz .LBB0_304
	v_readlane_b32 s18, v253, 57
	s_mov_b32 s10, 6
	v_readlane_b32 s19, v253, 58
	v_readlane_b32 s11, v253, 26
	s_branch .LBB0_292

.Lfftb_stage:
	s_nop 7
	v_cndmask_b32_e64 v40, v236, v237, s[42:43]
	v_mul_f32_e32 v41, v40, v92
	v_mul_f32_e32 v42, v40, v88
	v_add_u32_e32 v43, 0x8800, v83
	ds_write2_b32 v43, v41, v42 offset1:16
	global_load_dwordx4 v[4:7], v[0:1], off
	v_mul_f32_e32 v41, v40, v93
	v_mul_f32_e32 v42, v40, v89
	ds_write2_b32 v43, v41, v42 offset0:68 offset1:84
	v_mul_f32_e32 v41, v40, v94
	v_mul_f32_e32 v42, v40, v90
	ds_write2_b32 v43, v41, v42 offset0:136 offset1:152
	v_mul_f32_e32 v41, v40, v95
	v_mul_f32_e32 v42, v40, v91
	global_load_dwordx4 v[0:3], v[0:1], off offset:1024
	ds_write2_b32 v43, v41, v42 offset0:204 offset1:220
	v_mul_f32_e32 v41, v40, v100
	v_mul_f32_e32 v42, v40, v96
	v_add_u32_e32 v43, 0x9800, v83
	ds_write2_b32 v43, v41, v42 offset0:64 offset1:80
	v_mul_f32_e32 v41, v40, v101
	v_mul_f32_e32 v42, v40, v97
	ds_write2_b32 v43, v41, v42 offset0:132 offset1:148
	global_load_dwordx4 v[12:15], v[8:9], off
	v_mul_f32_e32 v41, v40, v102
	v_mul_f32_e32 v42, v40, v98
	ds_write2_b32 v43, v41, v42 offset0:200 offset1:216
	v_mul_f32_e32 v41, v40, v103
	v_mul_f32_e32 v42, v40, v99
	v_add_u32_e32 v43, 0x9c00, v83
	ds_write2_b32 v43, v41, v42 offset0:12 offset1:28
	v_mul_f32_e32 v41, v40, v108
	global_load_dwordx4 v[8:11], v[8:9], off offset:1024
	v_mul_f32_e32 v42, v40, v104
	v_add_u32_e32 v43, 0xa800, v83
	ds_write2_b32 v43, v41, v42 offset0:128 offset1:144
	v_mul_f32_e32 v41, v40, v109
	v_mul_f32_e32 v42, v40, v105
	ds_write2_b32 v43, v41, v42 offset0:196 offset1:212
	v_mul_f32_e32 v41, v40, v110
	v_mul_f32_e32 v42, v40, v106
	global_load_dwordx4 v[20:23], v[16:17], off
	v_add_u32_e32 v43, 0xac00, v83
	ds_write2_b32 v43, v41, v42 offset0:8 offset1:24
	v_mul_f32_e32 v41, v40, v111
	v_mul_f32_e32 v42, v40, v107
	ds_write2_b32 v43, v41, v42 offset0:76 offset1:92
	v_mul_f32_e32 v32, v40, v32
	v_mul_f32_e32 v36, v40, v36
	v_add_u32_e32 v41, 0xb800, v83
	global_load_dwordx4 v[16:19], v[16:17], off offset:1024
	ds_write2_b32 v41, v32, v36 offset0:192 offset1:208
	v_mul_f32_e32 v32, v40, v33
	v_mul_f32_e32 v33, v40, v37
	v_add_u32_e32 v36, 0xbc00, v83
	ds_write2_b32 v36, v32, v33 offset0:4 offset1:20
	v_mul_f32_e32 v32, v40, v34
	v_mul_f32_e32 v33, v40, v38
	ds_write2_b32 v36, v32, v33 offset0:72 offset1:88
	global_load_dwordx4 v[28:31], v[24:25], off
	v_mul_f32_e32 v32, v40, v35
	v_mul_f32_e32 v33, v40, v39
	ds_write2_b32 v36, v32, v33 offset0:140 offset1:156
	global_load_dwordx4 v[24:27], v[24:25], off offset:1024
	v_add_u32_e32 v32, s0, v72
	v_add_u32_e32 v33, s20, v71
	v_cndmask_b32_e64 v40, v33, v32, s[42:43]
	v_ashrrev_i32_e32 v41, 31, v40
	v_lshlrev_b64 v[40:41], 11, v[40:41]
	v_lshl_add_u64 v[40:41], s[60:61], 0, v[40:41]
	v_lshl_add_u64 v[40:41], v[40:41], 0, s[36:37]
	v_mov_b32_e32 v65, v209
	v_lshl_add_u64 v[40:41], v[40:41], 0, v[64:65]
	v_add_co_u32_e32 v44, vcc, s1, v40
	s_waitcnt lgkmcnt(0)
	s_nop 0
	v_addc_co_u32_e32 v45, vcc, 0, v41, vcc
	s_barrier
	ds_read_b128 v[32:35], v84 offset:34816
	ds_read_b128 v[36:39], v84 offset:34832
	s_waitcnt lgkmcnt(1)
	v_mov_b32_e32 v49, v34
	v_mov_b32_e32 v34, v33
	v_mov_b32_e32 v48, v32
	s_waitcnt vmcnt(11)
	v_mov_b32_e32 v40, v116
	v_mov_b32_e32 v41, v117
	v_mov_b32_e32 v42, v118
	v_mov_b32_e32 v43, v119
	v_lshlrev_b32_e32 v47, 16, v41
	v_lshlrev_b32_e32 v46, 16, v40
	v_and_b32_e32 v41, 0xffff0000, v41
	v_and_b32_e32 v40, 0xffff0000, v40
	v_pk_mul_f32 v[32:33], v[34:35], v[40:41]
	v_lshlrev_b32_e32 v35, 16, v43
	v_lshlrev_b32_e32 v34, 16, v42
	s_waitcnt lgkmcnt(0)
	v_mov_b32_e32 v40, v36
	v_mov_b32_e32 v41, v38
	v_pk_mul_f32 v[34:35], v[40:41], v[34:35]
	v_and_b32_e32 v41, 0xffff0000, v43
	v_and_b32_e32 v40, 0xffff0000, v42
	v_mov_b32_e32 v38, v37
	v_pk_mul_f32 v[36:37], v[38:39], v[40:41]
	v_pk_mul_f32 v[46:47], v[48:49], v[46:47]
	v_bfe_u32 v38, v37, 16, 1
	v_bfe_u32 v39, v36, 16, 1
	v_bfe_u32 v40, v33, 16, 1
	v_bfe_u32 v41, v32, 16, 1
	v_add3_u32 v32, v32, v41, s3
	v_add3_u32 v33, v33, v40, s3
	v_add3_u32 v36, v36, v39, s3
	v_add3_u32 v37, v37, v38, s3
	v_bfe_u32 v38, v46, 16, 1
	v_bfe_u32 v39, v47, 16, 1
	v_bfe_u32 v40, v34, 16, 1
	v_bfe_u32 v41, v35, 16, 1
	v_add3_u32 v35, v35, v41, s3
	v_add3_u32 v34, v34, v40, s3
	v_add3_u32 v39, v47, v39, s3
	v_add3_u32 v38, v46, v38, s3
	v_lshrrev_b32_e32 v38, 16, v38
	v_lshrrev_b32_e32 v39, 16, v39
	v_lshrrev_b32_e32 v34, 16, v34
	v_lshrrev_b32_e32 v35, 16, v35
	v_and_or_b32 v35, v37, s23, v35
	v_and_or_b32 v34, v36, s23, v34
	v_and_or_b32 v33, v33, s23, v39
	v_and_or_b32 v32, v32, s23, v38
	global_store_dwordx4 v[44:45], v[32:35], off offset:1024 sc1
	s_nop 1
	v_add_u32_e32 v32, s0, v74
	v_add_u32_e32 v33, s20, v73
	v_cndmask_b32_e64 v40, v33, v32, s[42:43]
	v_ashrrev_i32_e32 v41, 31, v40
	v_lshlrev_b64 v[40:41], 11, v[40:41]
	v_lshl_add_u64 v[40:41], s[60:61], 0, v[40:41]
	v_lshl_add_u64 v[40:41], v[40:41], 0, s[36:37]
	v_lshl_add_u64 v[40:41], v[40:41], 0, v[64:65]
	v_add_co_u32_e32 v44, vcc, s1, v40
	ds_read_b128 v[32:35], v85 offset:34816
	ds_read_b128 v[36:39], v85 offset:34832
	v_addc_co_u32_e32 v45, vcc, 0, v41, vcc
	s_waitcnt lgkmcnt(1)
	v_mov_b32_e32 v49, v34
	v_mov_b32_e32 v34, v33
	v_mov_b32_e32 v48, v32
	s_waitcnt vmcnt(11)
	v_mov_b32_e32 v40, v120
	v_mov_b32_e32 v41, v121
	v_mov_b32_e32 v42, v122
	v_mov_b32_e32 v43, v123
	v_lshlrev_b32_e32 v47, 16, v41
	v_lshlrev_b32_e32 v46, 16, v40
	v_and_b32_e32 v41, 0xffff0000, v41
	v_and_b32_e32 v40, 0xffff0000, v40
	v_pk_mul_f32 v[32:33], v[34:35], v[40:41]
	v_lshlrev_b32_e32 v35, 16, v43
	v_lshlrev_b32_e32 v34, 16, v42
	s_waitcnt lgkmcnt(0)
	v_mov_b32_e32 v40, v36
	v_mov_b32_e32 v41, v38
	v_pk_mul_f32 v[34:35], v[40:41], v[34:35]
	v_and_b32_e32 v41, 0xffff0000, v43
	v_and_b32_e32 v40, 0xffff0000, v42
	v_mov_b32_e32 v38, v37
	v_pk_mul_f32 v[36:37], v[38:39], v[40:41]
	v_pk_mul_f32 v[46:47], v[48:49], v[46:47]
	v_bfe_u32 v38, v37, 16, 1
	v_bfe_u32 v39, v36, 16, 1
	v_bfe_u32 v40, v33, 16, 1
	v_bfe_u32 v41, v32, 16, 1
	v_add3_u32 v32, v32, v41, s3
	v_add3_u32 v33, v33, v40, s3
	v_add3_u32 v36, v36, v39, s3
	v_add3_u32 v37, v37, v38, s3
	v_bfe_u32 v38, v46, 16, 1
	v_bfe_u32 v39, v47, 16, 1
	v_bfe_u32 v40, v34, 16, 1
	v_bfe_u32 v41, v35, 16, 1
	v_add3_u32 v35, v35, v41, s3
	v_add3_u32 v34, v34, v40, s3
	v_add3_u32 v39, v47, v39, s3
	v_add3_u32 v38, v46, v38, s3
	v_lshrrev_b32_e32 v38, 16, v38
	v_lshrrev_b32_e32 v39, 16, v39
	v_lshrrev_b32_e32 v34, 16, v34
	v_lshrrev_b32_e32 v35, 16, v35
	v_and_or_b32 v35, v37, s23, v35
	v_and_or_b32 v34, v36, s23, v34
	v_and_or_b32 v33, v33, s23, v39
	v_and_or_b32 v32, v32, s23, v38
	global_store_dwordx4 v[44:45], v[32:35], off offset:1024 sc1
	s_nop 1
	v_add_u32_e32 v32, s0, v76
	v_add_u32_e32 v33, s20, v75
	v_cndmask_b32_e64 v40, v33, v32, s[42:43]
	v_ashrrev_i32_e32 v41, 31, v40
	v_lshlrev_b64 v[40:41], 11, v[40:41]
	v_lshl_add_u64 v[40:41], s[60:61], 0, v[40:41]
	v_lshl_add_u64 v[40:41], v[40:41], 0, s[36:37]
	v_lshl_add_u64 v[40:41], v[40:41], 0, v[64:65]
	v_add_co_u32_e32 v44, vcc, s1, v40
	ds_read_b128 v[32:35], v86 offset:34816
	ds_read_b128 v[36:39], v86 offset:34832
	v_addc_co_u32_e32 v45, vcc, 0, v41, vcc
	s_waitcnt lgkmcnt(1)
	v_mov_b32_e32 v49, v34
	v_mov_b32_e32 v34, v33
	v_mov_b32_e32 v48, v32
	s_waitcnt vmcnt(11)
	v_mov_b32_e32 v40, v124
	v_mov_b32_e32 v41, v125
	v_mov_b32_e32 v42, v126
	v_mov_b32_e32 v43, v127
	v_lshlrev_b32_e32 v47, 16, v41
	v_lshlrev_b32_e32 v46, 16, v40
	v_and_b32_e32 v41, 0xffff0000, v41
	v_and_b32_e32 v40, 0xffff0000, v40
	v_pk_mul_f32 v[32:33], v[34:35], v[40:41]
	v_lshlrev_b32_e32 v35, 16, v43
	v_lshlrev_b32_e32 v34, 16, v42
	s_waitcnt lgkmcnt(0)
	v_mov_b32_e32 v40, v36
	v_mov_b32_e32 v41, v38
	v_pk_mul_f32 v[34:35], v[40:41], v[34:35]
	v_and_b32_e32 v41, 0xffff0000, v43
	v_and_b32_e32 v40, 0xffff0000, v42
	v_mov_b32_e32 v38, v37
	v_pk_mul_f32 v[36:37], v[38:39], v[40:41]
	v_pk_mul_f32 v[46:47], v[48:49], v[46:47]
	v_bfe_u32 v38, v37, 16, 1
	v_bfe_u32 v39, v36, 16, 1
	v_bfe_u32 v40, v33, 16, 1
	v_bfe_u32 v41, v32, 16, 1
	v_add3_u32 v32, v32, v41, s3
	v_add3_u32 v33, v33, v40, s3
	v_add3_u32 v36, v36, v39, s3
	v_add3_u32 v37, v37, v38, s3
	v_bfe_u32 v38, v46, 16, 1
	v_bfe_u32 v39, v47, 16, 1
	v_bfe_u32 v40, v34, 16, 1
	v_bfe_u32 v41, v35, 16, 1
	v_add3_u32 v35, v35, v41, s3
	v_add3_u32 v34, v34, v40, s3
	v_add3_u32 v39, v47, v39, s3
	v_add3_u32 v38, v46, v38, s3
	v_lshrrev_b32_e32 v38, 16, v38
	v_lshrrev_b32_e32 v39, 16, v39
	v_lshrrev_b32_e32 v34, 16, v34
	v_lshrrev_b32_e32 v35, 16, v35
	v_and_or_b32 v35, v37, s23, v35
	v_and_or_b32 v34, v36, s23, v34
	v_and_or_b32 v33, v33, s23, v39
	v_and_or_b32 v32, v32, s23, v38
	global_store_dwordx4 v[44:45], v[32:35], off offset:1024 sc1
	s_nop 1
	v_add_u32_e32 v32, s0, v78
	v_add_u32_e32 v33, s20, v77
	v_cndmask_b32_e64 v40, v33, v32, s[42:43]
	v_ashrrev_i32_e32 v41, 31, v40
	v_lshlrev_b64 v[40:41], 11, v[40:41]
	v_lshl_add_u64 v[40:41], s[60:61], 0, v[40:41]
	v_lshl_add_u64 v[40:41], v[40:41], 0, s[36:37]
	v_lshl_add_u64 v[40:41], v[40:41], 0, v[64:65]
	v_add_co_u32_e32 v44, vcc, s1, v40
	ds_read_b128 v[32:35], v87 offset:34816
	ds_read_b128 v[36:39], v87 offset:34832
	v_addc_co_u32_e32 v45, vcc, 0, v41, vcc
	s_waitcnt lgkmcnt(1)
	v_mov_b32_e32 v49, v34
	v_mov_b32_e32 v34, v33
	v_mov_b32_e32 v48, v32
	s_mul_i32 s0, s17, s54
	s_add_i32 s16, s0, s7
	s_cmpk_lt_i32 s16, 0x480
	s_waitcnt vmcnt(11)
	v_mov_b32_e32 v40, v128
	v_mov_b32_e32 v41, v129
	v_mov_b32_e32 v42, v130
	v_mov_b32_e32 v43, v131
	v_lshlrev_b32_e32 v47, 16, v41
	v_lshlrev_b32_e32 v46, 16, v40
	v_and_b32_e32 v41, 0xffff0000, v41
	v_and_b32_e32 v40, 0xffff0000, v40
	v_pk_mul_f32 v[32:33], v[34:35], v[40:41]
	v_lshlrev_b32_e32 v35, 16, v43
	v_lshlrev_b32_e32 v34, 16, v42
	s_waitcnt lgkmcnt(0)
	v_mov_b32_e32 v40, v36
	v_mov_b32_e32 v41, v38
	v_pk_mul_f32 v[34:35], v[40:41], v[34:35]
	v_and_b32_e32 v41, 0xffff0000, v43
	v_and_b32_e32 v40, 0xffff0000, v42
	v_mov_b32_e32 v38, v37
	v_pk_mul_f32 v[36:37], v[38:39], v[40:41]
	v_pk_mul_f32 v[46:47], v[48:49], v[46:47]
	v_bfe_u32 v38, v37, 16, 1
	v_bfe_u32 v39, v36, 16, 1
	v_bfe_u32 v40, v33, 16, 1
	v_bfe_u32 v41, v32, 16, 1
	v_add3_u32 v32, v32, v41, s3
	v_add3_u32 v33, v33, v40, s3
	v_add3_u32 v36, v36, v39, s3
	v_add3_u32 v37, v37, v38, s3
	v_bfe_u32 v38, v46, 16, 1
	v_bfe_u32 v39, v47, 16, 1
	v_bfe_u32 v40, v34, 16, 1
	v_bfe_u32 v41, v35, 16, 1
	v_add3_u32 v35, v35, v41, s3
	v_add3_u32 v34, v34, v40, s3
	v_add3_u32 v39, v47, v39, s3
	v_add3_u32 v38, v46, v38, s3
	v_lshrrev_b32_e32 v38, 16, v38
	v_lshrrev_b32_e32 v39, 16, v39
	v_lshrrev_b32_e32 v34, 16, v34
	v_lshrrev_b32_e32 v35, 16, v35
	v_and_or_b32 v35, v37, s23, v35
	v_and_or_b32 v34, v36, s23, v34
	v_and_or_b32 v33, v33, s23, v39
	v_and_or_b32 v32, v32, s23, v38
	global_store_dwordx4 v[44:45], v[32:35], off offset:1024 sc1
	s_cbranch_scc0 .LBB0_426

.LBB0_731:
	s_lshl_b32 s24, s15, 1
	s_lshl_b32 s21, s2, 1
	v_or_b32_e32 v39, s24, v0
	s_add_i32 s26, s24, 4
	v_or_b32_e32 v38, s21, v1
	s_add_i32 s25, s21, 4
	s_add_i32 s30, s24, 8
	v_add_lshl_u32 v208, v39, v8, 10
	v_or_b32_e32 v41, s26, v0
	v_mov_b32_e32 v19, v209
	s_add_i32 s33, s24, 12
	v_add_lshl_u32 v18, v38, v3, 10
	v_or_b32_e32 v40, s25, v1
	v_or_b32_e32 v43, s30, v0
	v_lshl_add_u64 v[34:35], v[208:209], 2, v[10:11]
	v_add_lshl_u32 v208, v41, v8, 10
	v_mov_b32_e32 v21, v209
	s_add_i32 s27, s21, 8
	s_add_i32 s31, s21, 12
	s_add_i32 s50, s24, 16
	v_or_b32_e32 v45, s33, v0
	v_lshl_add_u64 v[18:19], v[18:19], 2, v[10:11]
	v_add_lshl_u32 v20, v40, v3, 10
	v_lshl_add_u64 v[36:37], v[208:209], 2, v[10:11]
	v_add_lshl_u32 v208, v43, v8, 10
	s_add_i32 s56, s24, 20
	v_or_b32_e32 v42, s27, v1
	v_or_b32_e32 v44, s31, v1
	v_or_b32_e32 v47, s50, v0
	v_lshl_add_u64 v[20:21], v[20:21], 2, v[10:11]
	global_load_dword v54, v[34:35], off
	global_load_dword v55, v[18:19], off
	global_load_dword v56, v[36:37], off
	global_load_dword v57, v[20:21], off
	v_lshl_add_u64 v[18:19], v[208:209], 2, v[10:11]
	v_add_lshl_u32 v208, v45, v8, 10
	v_mov_b32_e32 v23, v209
	v_mov_b32_e32 v25, v209
	s_add_i32 s36, s21, 16
	s_add_i32 s51, s21, 20
	s_add_i32 s58, s24, 24
	v_or_b32_e32 v49, s56, v0
	v_add_lshl_u32 v22, v42, v3, 10
	v_add_lshl_u32 v24, v44, v3, 10
	v_lshl_add_u64 v[20:21], v[208:209], 2, v[10:11]
	v_add_lshl_u32 v208, v47, v8, 10
	s_add_i32 s57, s21, 24
	s_add_i32 s21, s21, 28
	s_add_i32 s24, s24, 28
	v_or_b32_e32 v46, s36, v1
	v_or_b32_e32 v48, s51, v1
	v_or_b32_e32 v51, s58, v0
	v_lshl_add_u64 v[22:23], v[22:23], 2, v[10:11]
	v_lshl_add_u64 v[24:25], v[24:25], 2, v[10:11]
	global_load_dword v58, v[18:19], off
	global_load_dword v59, v[22:23], off
	global_load_dword v60, v[20:21], off
	global_load_dword v61, v[24:25], off
	v_lshl_add_u64 v[18:19], v[208:209], 2, v[10:11]
	v_add_lshl_u32 v208, v49, v8, 10
	v_mov_b32_e32 v27, v209
	v_mov_b32_e32 v29, v209
	v_or_b32_e32 v50, s57, v1
	v_or_b32_e32 v52, s21, v1
	v_or_b32_e32 v53, s24, v0
	v_add_lshl_u32 v26, v46, v3, 10
	v_add_lshl_u32 v28, v48, v3, 10
	v_lshl_add_u64 v[20:21], v[208:209], 2, v[10:11]
	v_add_lshl_u32 v208, v51, v8, 10
	v_mov_b32_e32 v31, v209
	v_mov_b32_e32 v33, v209
	v_add_lshl_u32 v30, v50, v3, 10
	v_add_lshl_u32 v32, v52, v3, 10
	v_lshl_add_u64 v[26:27], v[26:27], 2, v[10:11]
	v_lshl_add_u64 v[28:29], v[28:29], 2, v[10:11]
	global_load_dword v62, v[18:19], off
	global_load_dword v63, v[26:27], off
	global_load_dword v64, v[20:21], off
	global_load_dword v65, v[28:29], off
	v_lshl_add_u64 v[18:19], v[208:209], 2, v[10:11]
	v_add_lshl_u32 v208, v53, v8, 10
	v_lshl_add_u64 v[30:31], v[30:31], 2, v[10:11]
	v_lshl_add_u64 v[32:33], v[32:33], 2, v[10:11]
	v_lshl_add_u64 v[20:21], v[208:209], 2, v[10:11]
	global_load_dword v66, v[18:19], off
	global_load_dword v67, v[30:31], off
	global_load_dword v68, v[20:21], off
	global_load_dword v69, v[32:33], off
	s_add_i32 s15, s15, 16
	s_add_i32 s2, s2, 16
	s_add_i32 s20, s20, -16
	v_mad_u64_u32 v[18:19], s[24:25], v39, s8, v[2:3]
	s_cmp_lg_u32 s20, 0
	v_mad_u64_u32 v[20:21], s[24:25], v38, s8, v[2:3]
	v_mad_u64_u32 v[22:23], s[24:25], v41, s8, v[2:3]
	v_mad_u64_u32 v[24:25], s[24:25], v40, s8, v[2:3]
	v_mad_u64_u32 v[26:27], s[24:25], v43, s8, v[2:3]
	v_mad_u64_u32 v[28:29], s[24:25], v42, s8, v[2:3]
	v_mad_u64_u32 v[30:31], s[24:25], v45, s8, v[2:3]
	v_mad_u64_u32 v[32:33], s[24:25], v44, s8, v[2:3]
	v_mad_u64_u32 v[34:35], s[24:25], v47, s8, v[2:3]
	v_mad_u64_u32 v[36:37], s[24:25], v46, s8, v[2:3]
	v_mad_u64_u32 v[38:39], s[24:25], v49, s8, v[2:3]
	v_mad_u64_u32 v[40:41], s[24:25], v48, s8, v[2:3]
	v_mad_u64_u32 v[42:43], s[24:25], v51, s8, v[2:3]
	v_mad_u64_u32 v[44:45], s[24:25], v50, s8, v[2:3]
	v_mad_u64_u32 v[46:47], s[24:25], v53, s8, v[2:3]
	v_mad_u64_u32 v[48:49], s[24:25], v52, s8, v[2:3]
	s_waitcnt vmcnt(15)
	ds_write_b32 v18, v54
	s_waitcnt vmcnt(14)
	ds_write_b32 v20, v55
	s_waitcnt vmcnt(13)
	ds_write_b32 v22, v56
	s_waitcnt vmcnt(12)
	ds_write_b32 v24, v57
	s_waitcnt vmcnt(11)
	ds_write_b32 v26, v58
	s_waitcnt vmcnt(10)
	ds_write_b32 v28, v59
	s_waitcnt vmcnt(9)
	ds_write_b32 v30, v60
	s_waitcnt vmcnt(8)
	ds_write_b32 v32, v61
	s_waitcnt vmcnt(7)
	ds_write_b32 v34, v62
	s_waitcnt vmcnt(6)
	ds_write_b32 v36, v63
	s_waitcnt vmcnt(5)
	ds_write_b32 v38, v64
	s_waitcnt vmcnt(4)
	ds_write_b32 v40, v65
	s_waitcnt vmcnt(3)
	ds_write_b32 v42, v66
	s_waitcnt vmcnt(2)
	ds_write_b32 v44, v67
	s_waitcnt vmcnt(1)
	ds_write_b32 v46, v68
	s_waitcnt vmcnt(0)
	ds_write_b32 v48, v69
	s_cbranch_scc1 .LBB0_731
	s_waitcnt lgkmcnt(0)
	ds_read2_b32 v[10:11], v13 offset1:8
	ds_read2_b32 v[22:23], v13 offset0:33 offset1:41
	ds_read2_b32 v[24:25], v13 offset0:66 offset1:74
	ds_read2_b32 v[26:27], v13 offset0:99 offset1:107
	v_lshlrev_b32_e32 v208, 1, v8
	s_waitcnt lgkmcnt(3)
	v_bfe_u32 v3, v10, 16, 1
	v_add3_u32 v3, v10, v3, s3
	s_waitcnt lgkmcnt(2)
	v_bfe_u32 v8, v22, 16, 1
	ds_read2_b32 v[28:29], v13 offset0:132 offset1:140
	v_lshrrev_b32_e32 v3, 16, v3
	v_add3_u32 v8, v22, v8, s3
	ds_read2_b32 v[30:31], v13 offset0:165 offset1:173
	v_and_or_b32 v18, v8, s23, v3
	s_waitcnt lgkmcnt(3)
	v_bfe_u32 v3, v24, 16, 1
	v_add3_u32 v3, v24, v3, s3
	s_waitcnt lgkmcnt(2)
	v_bfe_u32 v8, v26, 16, 1
	ds_read2_b32 v[32:33], v13 offset0:198 offset1:206
	v_lshrrev_b32_e32 v3, 16, v3
	v_add3_u32 v8, v26, v8, s3
	ds_read2_b32 v[34:35], v13 offset0:231 offset1:239
	v_and_or_b32 v19, v8, s23, v3
	s_waitcnt lgkmcnt(3)
	v_bfe_u32 v3, v28, 16, 1
	v_add3_u32 v3, v28, v3, s3
	s_waitcnt lgkmcnt(2)
	v_bfe_u32 v8, v30, 16, 1
	v_lshrrev_b32_e32 v3, 16, v3
	v_add3_u32 v8, v30, v8, s3
	v_and_or_b32 v20, v8, s23, v3
	s_waitcnt lgkmcnt(1)
	v_bfe_u32 v3, v32, 16, 1
	v_lshlrev_b64 v[6:7], 21, v[6:7]
	v_add3_u32 v3, v32, v3, s3
	s_waitcnt lgkmcnt(0)
	v_bfe_u32 v8, v34, 16, 1
	v_lshl_add_u64 v[6:7], s[16:17], 0, v[6:7]
	v_lshrrev_b32_e32 v3, 16, v3
	v_add3_u32 v8, v34, v8, s3
	v_or_b32_e32 v36, v17, v12
	v_lshl_add_u64 v[6:7], v[6:7], 0, v[208:209]
	v_lshlrev_b32_e32 v208, 1, v4
	v_and_or_b32 v21, v8, s23, v3
	v_ashrrev_i32_e32 v37, 31, v36
	v_bfe_u32 v3, v11, 16, 1
	v_lshl_add_u64 v[6:7], v[6:7], 0, v[208:209]
	v_lshlrev_b64 v[36:37], 11, v[36:37]
	v_add3_u32 v3, v11, v3, s3
	v_bfe_u32 v8, v23, 16, 1
	v_lshl_add_u64 v[36:37], v[6:7], 0, v[36:37]
	v_lshrrev_b32_e32 v3, 16, v3
	v_add3_u32 v8, v23, v8, s3
	global_store_dwordx4 v[36:37], v[18:21], off sc1
	v_or_b32_e32 v10, v17, v14
	v_ashrrev_i32_e32 v11, 31, v10
	v_and_or_b32 v18, v8, s23, v3
	v_bfe_u32 v3, v25, 16, 1
	v_add3_u32 v3, v25, v3, s3
	v_bfe_u32 v8, v27, 16, 1
	v_lshrrev_b32_e32 v3, 16, v3
	v_add3_u32 v8, v27, v8, s3
	v_and_or_b32 v19, v8, s23, v3
	v_bfe_u32 v3, v29, 16, 1
	v_add3_u32 v3, v29, v3, s3
	v_bfe_u32 v8, v31, 16, 1
	v_lshrrev_b32_e32 v3, 16, v3
	v_add3_u32 v8, v31, v8, s3
	v_and_or_b32 v20, v8, s23, v3
	v_bfe_u32 v3, v33, 16, 1
	v_add3_u32 v3, v33, v3, s3
	v_bfe_u32 v8, v35, 16, 1
	v_lshrrev_b32_e32 v3, 16, v3
	v_add3_u32 v8, v35, v8, s3
	v_lshlrev_b64 v[10:11], 11, v[10:11]
	v_and_or_b32 v21, v8, s23, v3
	ds_read2_b32 v[22:23], v13 offset0:16 offset1:24
	v_lshl_add_u64 v[10:11], v[6:7], 0, v[10:11]
	global_store_dwordx4 v[10:11], v[18:21], off sc1
	ds_read2_b32 v[10:11], v13 offset0:49 offset1:57
	ds_read2_b32 v[24:25], v13 offset0:82 offset1:90
	ds_read2_b32 v[26:27], v13 offset0:115 offset1:123
	s_waitcnt lgkmcnt(3)
	v_bfe_u32 v3, v22, 16, 1
	v_add3_u32 v3, v22, v3, s3
	s_waitcnt lgkmcnt(2)
	v_bfe_u32 v8, v10, 16, 1
	ds_read2_b32 v[28:29], v13 offset0:148 offset1:156
	v_lshrrev_b32_e32 v3, 16, v3
	v_add3_u32 v8, v10, v8, s3
	ds_read2_b32 v[30:31], v13 offset0:181 offset1:189
	v_and_or_b32 v18, v8, s23, v3
	s_waitcnt lgkmcnt(3)
	v_bfe_u32 v3, v24, 16, 1
	v_add3_u32 v3, v24, v3, s3
	s_waitcnt lgkmcnt(2)
	v_bfe_u32 v8, v26, 16, 1
	ds_read2_b32 v[32:33], v13 offset0:214 offset1:222
	v_lshrrev_b32_e32 v3, 16, v3
	v_add3_u32 v8, v26, v8, s3
	ds_read2_b32 v[34:35], v13 offset0:247 offset1:255
	v_and_or_b32 v19, v8, s23, v3
	s_waitcnt lgkmcnt(3)
	v_bfe_u32 v3, v28, 16, 1
	v_add3_u32 v3, v28, v3, s3
	s_waitcnt lgkmcnt(2)
	v_bfe_u32 v8, v30, 16, 1
	v_lshrrev_b32_e32 v3, 16, v3
	v_add3_u32 v8, v30, v8, s3
	v_and_or_b32 v20, v8, s23, v3
	s_waitcnt lgkmcnt(1)
	v_bfe_u32 v3, v32, 16, 1
	v_add3_u32 v3, v32, v3, s3
	s_waitcnt lgkmcnt(0)
	v_bfe_u32 v8, v34, 16, 1
	v_lshrrev_b32_e32 v3, 16, v3
	v_add3_u32 v8, v34, v8, s3
	v_or_b32_e32 v36, v17, v15
	v_and_or_b32 v21, v8, s23, v3
	v_ashrrev_i32_e32 v37, 31, v36
	v_bfe_u32 v3, v23, 16, 1
	v_lshlrev_b64 v[36:37], 11, v[36:37]
	v_add3_u32 v3, v23, v3, s3
	v_bfe_u32 v8, v11, 16, 1
	v_lshl_add_u64 v[36:37], v[6:7], 0, v[36:37]
	v_lshrrev_b32_e32 v3, 16, v3
	v_add3_u32 v8, v11, v8, s3
	global_store_dwordx4 v[36:37], v[18:21], off sc1
	v_or_b32_e32 v10, v17, v16
	v_ashrrev_i32_e32 v11, 31, v10
	v_and_or_b32 v18, v8, s23, v3
	v_bfe_u32 v3, v25, 16, 1
	v_add3_u32 v3, v25, v3, s3
	v_bfe_u32 v8, v27, 16, 1
	v_lshrrev_b32_e32 v3, 16, v3
	v_add3_u32 v8, v27, v8, s3
	v_and_or_b32 v19, v8, s23, v3
	v_bfe_u32 v3, v29, 16, 1
	v_add3_u32 v3, v29, v3, s3
	v_bfe_u32 v8, v31, 16, 1
	v_lshrrev_b32_e32 v3, 16, v3
	v_add3_u32 v8, v31, v8, s3
	v_and_or_b32 v20, v8, s23, v3
	v_bfe_u32 v3, v33, 16, 1
	v_add3_u32 v3, v33, v3, s3
	v_bfe_u32 v8, v35, 16, 1
	v_lshrrev_b32_e32 v3, 16, v3
	v_add3_u32 v8, v35, v8, s3
	v_lshlrev_b64 v[10:11], 11, v[10:11]
	v_and_or_b32 v21, v8, s23, v3
	v_lshl_add_u64 v[6:7], v[6:7], 0, v[10:11]
	global_store_dwordx4 v[6:7], v[18:21], off sc1
	s_waitcnt lgkmcnt(0)
	s_mov_b32 s33, 0x9000

.LBB0_735:
	s_lshl_b32 s24, s15, 1
	s_lshl_b32 s21, s2, 1
	v_or_b32_e32 v19, s24, v0
	s_add_i32 s26, s24, 4
	v_or_b32_e32 v7, s21, v1
	s_add_i32 s25, s21, 4
	s_add_i32 s30, s24, 8
	v_add_lshl_u32 v208, v19, v8, 10
	v_or_b32_e32 v41, s26, v0
	v_mov_b32_e32 v21, v209
	s_add_i32 s33, s24, 12
	v_add_lshl_u32 v20, v7, v3, 10
	v_or_b32_e32 v40, s25, v1
	v_or_b32_e32 v43, s30, v0
	v_lshl_add_u64 v[36:37], v[208:209], 2, v[10:11]
	v_add_lshl_u32 v208, v41, v8, 10
	v_mov_b32_e32 v23, v209
	s_add_i32 s27, s21, 8
	s_add_i32 s31, s21, 12
	s_add_i32 s50, s24, 16
	v_or_b32_e32 v45, s33, v0
	v_lshl_add_u64 v[20:21], v[20:21], 2, v[10:11]
	v_add_lshl_u32 v22, v40, v3, 10
	v_lshl_add_u64 v[38:39], v[208:209], 2, v[10:11]
	v_add_lshl_u32 v208, v43, v8, 10
	s_add_i32 s56, s24, 20
	v_or_b32_e32 v42, s27, v1
	v_or_b32_e32 v44, s31, v1
	v_or_b32_e32 v47, s50, v0
	v_lshl_add_u64 v[22:23], v[22:23], 2, v[10:11]
	global_load_dword v54, v[36:37], off
	global_load_dword v55, v[20:21], off
	global_load_dword v56, v[38:39], off
	global_load_dword v57, v[22:23], off
	v_lshl_add_u64 v[20:21], v[208:209], 2, v[10:11]
	v_add_lshl_u32 v208, v45, v8, 10
	v_mov_b32_e32 v25, v209
	v_mov_b32_e32 v27, v209
	s_add_i32 s36, s21, 16
	s_add_i32 s51, s21, 20
	s_add_i32 s58, s24, 24
	v_or_b32_e32 v49, s56, v0
	v_add_lshl_u32 v24, v42, v3, 10
	v_add_lshl_u32 v26, v44, v3, 10
	v_lshl_add_u64 v[22:23], v[208:209], 2, v[10:11]
	v_add_lshl_u32 v208, v47, v8, 10
	s_add_i32 s57, s21, 24
	s_add_i32 s21, s21, 28
	s_add_i32 s24, s24, 28
	v_or_b32_e32 v46, s36, v1
	v_or_b32_e32 v48, s51, v1
	v_or_b32_e32 v51, s58, v0
	v_lshl_add_u64 v[24:25], v[24:25], 2, v[10:11]
	v_lshl_add_u64 v[26:27], v[26:27], 2, v[10:11]
	global_load_dword v58, v[20:21], off
	global_load_dword v59, v[24:25], off
	global_load_dword v60, v[22:23], off
	global_load_dword v61, v[26:27], off
	v_lshl_add_u64 v[20:21], v[208:209], 2, v[10:11]
	v_add_lshl_u32 v208, v49, v8, 10
	v_mov_b32_e32 v29, v209
	v_mov_b32_e32 v31, v209
	v_or_b32_e32 v50, s57, v1
	v_or_b32_e32 v52, s21, v1
	v_or_b32_e32 v53, s24, v0
	v_add_lshl_u32 v28, v46, v3, 10
	v_add_lshl_u32 v30, v48, v3, 10
	v_lshl_add_u64 v[22:23], v[208:209], 2, v[10:11]
	v_add_lshl_u32 v208, v51, v8, 10
	v_mov_b32_e32 v33, v209
	v_mov_b32_e32 v35, v209
	v_add_lshl_u32 v32, v50, v3, 10
	v_add_lshl_u32 v34, v52, v3, 10
	v_lshl_add_u64 v[28:29], v[28:29], 2, v[10:11]
	v_lshl_add_u64 v[30:31], v[30:31], 2, v[10:11]
	global_load_dword v62, v[20:21], off
	global_load_dword v63, v[28:29], off
	global_load_dword v64, v[22:23], off
	global_load_dword v65, v[30:31], off
	v_lshl_add_u64 v[20:21], v[208:209], 2, v[10:11]
	v_add_lshl_u32 v208, v53, v8, 10
	v_lshl_add_u64 v[32:33], v[32:33], 2, v[10:11]
	v_lshl_add_u64 v[34:35], v[34:35], 2, v[10:11]
	v_lshl_add_u64 v[22:23], v[208:209], 2, v[10:11]
	global_load_dword v66, v[20:21], off
	global_load_dword v67, v[32:33], off
	global_load_dword v68, v[22:23], off
	global_load_dword v69, v[34:35], off
	s_add_i32 s15, s15, 16
	s_add_i32 s2, s2, 16
	s_add_i32 s20, s20, -16
	v_mad_u64_u32 v[20:21], s[24:25], v19, s8, v[2:3]
	s_cmp_lg_u32 s20, 0
	v_mad_u64_u32 v[22:23], s[24:25], v7, s8, v[2:3]
	v_mad_u64_u32 v[24:25], s[24:25], v41, s8, v[2:3]
	v_mad_u64_u32 v[26:27], s[24:25], v40, s8, v[2:3]
	v_mad_u64_u32 v[28:29], s[24:25], v43, s8, v[2:3]
	v_mad_u64_u32 v[30:31], s[24:25], v42, s8, v[2:3]
	v_mad_u64_u32 v[32:33], s[24:25], v45, s8, v[2:3]
	v_mad_u64_u32 v[34:35], s[24:25], v44, s8, v[2:3]
	v_mad_u64_u32 v[36:37], s[24:25], v47, s8, v[2:3]
	v_mad_u64_u32 v[38:39], s[24:25], v46, s8, v[2:3]
	v_mad_u64_u32 v[40:41], s[24:25], v49, s8, v[2:3]
	v_mad_u64_u32 v[42:43], s[24:25], v48, s8, v[2:3]
	v_mad_u64_u32 v[44:45], s[24:25], v51, s8, v[2:3]
	v_mad_u64_u32 v[46:47], s[24:25], v50, s8, v[2:3]
	v_mad_u64_u32 v[48:49], s[24:25], v53, s8, v[2:3]
	v_mad_u64_u32 v[50:51], s[24:25], v52, s8, v[2:3]
	s_waitcnt vmcnt(15)
	ds_write_b32 v20, v54
	s_waitcnt vmcnt(14)
	ds_write_b32 v22, v55
	s_waitcnt vmcnt(13)
	ds_write_b32 v24, v56
	s_waitcnt vmcnt(12)
	ds_write_b32 v26, v57
	s_waitcnt vmcnt(11)
	ds_write_b32 v28, v58
	s_waitcnt vmcnt(10)
	ds_write_b32 v30, v59
	s_waitcnt vmcnt(9)
	ds_write_b32 v32, v60
	s_waitcnt vmcnt(8)
	ds_write_b32 v34, v61
	s_waitcnt vmcnt(7)
	ds_write_b32 v36, v62
	s_waitcnt vmcnt(6)
	ds_write_b32 v38, v63
	s_waitcnt vmcnt(5)
	ds_write_b32 v40, v64
	s_waitcnt vmcnt(4)
	ds_write_b32 v42, v65
	s_waitcnt vmcnt(3)
	ds_write_b32 v44, v66
	s_waitcnt vmcnt(2)
	ds_write_b32 v46, v67
	s_waitcnt vmcnt(1)
	ds_write_b32 v48, v68
	s_waitcnt vmcnt(0)
	ds_write_b32 v50, v69
	s_cbranch_scc1 .LBB0_735
	v_cmp_eq_u32_e32 vcc, 1, v18
	v_mov_b32_e32 v3, 0x2100000
	v_mov_b32_e32 v10, 0x2500000
	v_ashrrev_i32_e32 v7, 31, v6
	v_cndmask_b32_e32 v208, v3, v10, vcc
	v_lshlrev_b64 v[6:7], 21, v[6:7]
	v_lshl_add_u64 v[10:11], s[10:11], 0, v[208:209]
	s_waitcnt lgkmcnt(0)
	v_lshl_add_u64 v[6:7], v[10:11], 0, v[6:7]
	ds_read2_b32 v[10:11], v13 offset1:8
	ds_read2_b32 v[22:23], v13 offset0:33 offset1:41
	ds_read2_b32 v[24:25], v13 offset0:66 offset1:74
	v_cmp_eq_u32_e32 vcc, 2, v18
	v_mov_b32_e32 v3, 0x400
	ds_read2_b32 v[26:27], v13 offset0:99 offset1:107
	v_cndmask_b32_e32 v208, 0, v3, vcc
	s_waitcnt lgkmcnt(3)
	v_bfe_u32 v3, v10, 16, 1
	v_lshl_add_u64 v[6:7], v[6:7], 0, v[208:209]
	v_lshlrev_b32_e32 v208, 1, v8
	v_add3_u32 v3, v10, v3, s3
	s_waitcnt lgkmcnt(2)
	v_bfe_u32 v8, v22, 16, 1
	ds_read2_b32 v[28:29], v13 offset0:132 offset1:140
	v_lshrrev_b32_e32 v3, 16, v3
	v_add3_u32 v8, v22, v8, s3
	ds_read2_b32 v[30:31], v13 offset0:165 offset1:173
	v_and_or_b32 v18, v8, s23, v3
	s_waitcnt lgkmcnt(3)
	v_bfe_u32 v3, v24, 16, 1
	v_add3_u32 v3, v24, v3, s3
	s_waitcnt lgkmcnt(2)
	v_bfe_u32 v8, v26, 16, 1
	ds_read2_b32 v[32:33], v13 offset0:198 offset1:206
	v_lshrrev_b32_e32 v3, 16, v3
	v_add3_u32 v8, v26, v8, s3
	ds_read2_b32 v[34:35], v13 offset0:231 offset1:239
	v_and_or_b32 v19, v8, s23, v3
	s_waitcnt lgkmcnt(3)
	v_bfe_u32 v3, v28, 16, 1
	v_add3_u32 v3, v28, v3, s3
	s_waitcnt lgkmcnt(2)
	v_bfe_u32 v8, v30, 16, 1
	v_lshrrev_b32_e32 v3, 16, v3
	v_add3_u32 v8, v30, v8, s3
	v_and_or_b32 v20, v8, s23, v3
	s_waitcnt lgkmcnt(1)
	v_bfe_u32 v3, v32, 16, 1
	v_add3_u32 v3, v32, v3, s3
	s_waitcnt lgkmcnt(0)
	v_bfe_u32 v8, v34, 16, 1
	v_lshrrev_b32_e32 v3, 16, v3
	v_add3_u32 v8, v34, v8, s3
	v_lshl_add_u64 v[6:7], v[6:7], 0, v[208:209]
	v_lshlrev_b32_e32 v208, 1, v4
	v_and_or_b32 v21, v8, s23, v3
	v_or_b32_e32 v3, v17, v12
	v_lshl_add_u64 v[6:7], v[6:7], 0, v[208:209]
	v_lshlrev_b32_e32 v208, 11, v3
	v_bfe_u32 v3, v11, 16, 1
	v_add3_u32 v3, v11, v3, s3
	v_bfe_u32 v8, v23, 16, 1
	v_lshl_add_u64 v[36:37], v[6:7], 0, v[208:209]
	v_lshrrev_b32_e32 v3, 16, v3
	v_add3_u32 v8, v23, v8, s3
	global_store_dwordx4 v[36:37], v[18:21], off sc1
	ds_read2_b32 v[10:11], v13 offset0:16 offset1:24
	s_mov_b32 s33, 0x9000
	v_and_or_b32 v18, v8, s23, v3
	v_bfe_u32 v3, v25, 16, 1
	v_add3_u32 v3, v25, v3, s3
	v_bfe_u32 v8, v27, 16, 1
	v_lshrrev_b32_e32 v3, 16, v3
	v_add3_u32 v8, v27, v8, s3
	v_and_or_b32 v19, v8, s23, v3
	v_bfe_u32 v3, v29, 16, 1
	v_add3_u32 v3, v29, v3, s3
	v_bfe_u32 v8, v31, 16, 1
	v_lshrrev_b32_e32 v3, 16, v3
	v_add3_u32 v8, v31, v8, s3
	v_and_or_b32 v20, v8, s23, v3
	v_bfe_u32 v3, v33, 16, 1
	v_add3_u32 v3, v33, v3, s3
	v_bfe_u32 v8, v35, 16, 1
	v_lshrrev_b32_e32 v3, 16, v3
	v_add3_u32 v8, v35, v8, s3
	v_and_or_b32 v21, v8, s23, v3
	v_or_b32_e32 v3, v17, v14
	v_lshlrev_b32_e32 v208, 11, v3
	v_lshl_add_u64 v[22:23], v[6:7], 0, v[208:209]
	global_store_dwordx4 v[22:23], v[18:21], off sc1
	ds_read2_b32 v[22:23], v13 offset0:49 offset1:57
	ds_read2_b32 v[24:25], v13 offset0:82 offset1:90
	ds_read2_b32 v[26:27], v13 offset0:115 offset1:123
	s_waitcnt lgkmcnt(3)
	v_bfe_u32 v3, v10, 16, 1
	v_add3_u32 v3, v10, v3, s3
	s_waitcnt lgkmcnt(2)
	v_bfe_u32 v8, v22, 16, 1
	ds_read2_b32 v[28:29], v13 offset0:148 offset1:156
	v_lshrrev_b32_e32 v3, 16, v3
	v_add3_u32 v8, v22, v8, s3
	ds_read2_b32 v[30:31], v13 offset0:181 offset1:189
	v_and_or_b32 v18, v8, s23, v3
	s_waitcnt lgkmcnt(3)
	v_bfe_u32 v3, v24, 16, 1
	v_add3_u32 v3, v24, v3, s3
	s_waitcnt lgkmcnt(2)
	v_bfe_u32 v8, v26, 16, 1
	ds_read2_b32 v[32:33], v13 offset0:214 offset1:222
	v_lshrrev_b32_e32 v3, 16, v3
	v_add3_u32 v8, v26, v8, s3
	ds_read2_b32 v[34:35], v13 offset0:247 offset1:255
	v_and_or_b32 v19, v8, s23, v3
	s_waitcnt lgkmcnt(3)
	v_bfe_u32 v3, v28, 16, 1
	v_add3_u32 v3, v28, v3, s3
	s_waitcnt lgkmcnt(2)
	v_bfe_u32 v8, v30, 16, 1
	v_lshrrev_b32_e32 v3, 16, v3
	v_add3_u32 v8, v30, v8, s3
	v_and_or_b32 v20, v8, s23, v3
	s_waitcnt lgkmcnt(1)
	v_bfe_u32 v3, v32, 16, 1
	v_add3_u32 v3, v32, v3, s3
	s_waitcnt lgkmcnt(0)
	v_bfe_u32 v8, v34, 16, 1
	v_lshrrev_b32_e32 v3, 16, v3
	v_add3_u32 v8, v34, v8, s3
	v_and_or_b32 v21, v8, s23, v3
	v_or_b32_e32 v3, v17, v15
	v_lshlrev_b32_e32 v208, 11, v3
	v_bfe_u32 v3, v11, 16, 1
	v_add3_u32 v3, v11, v3, s3
	v_bfe_u32 v8, v23, 16, 1
	v_lshl_add_u64 v[36:37], v[6:7], 0, v[208:209]
	v_lshrrev_b32_e32 v3, 16, v3
	v_add3_u32 v8, v23, v8, s3
	global_store_dwordx4 v[36:37], v[18:21], off sc1
	s_nop 1
	v_and_or_b32 v18, v8, s23, v3
	v_bfe_u32 v3, v25, 16, 1
	v_add3_u32 v3, v25, v3, s3
	v_bfe_u32 v8, v27, 16, 1
	v_lshrrev_b32_e32 v3, 16, v3
	v_add3_u32 v8, v27, v8, s3
	v_and_or_b32 v19, v8, s23, v3
	v_bfe_u32 v3, v29, 16, 1
	v_add3_u32 v3, v29, v3, s3
	v_bfe_u32 v8, v31, 16, 1
	v_lshrrev_b32_e32 v3, 16, v3
	v_add3_u32 v8, v31, v8, s3
	v_and_or_b32 v20, v8, s23, v3
	v_bfe_u32 v3, v33, 16, 1
	v_add3_u32 v3, v33, v3, s3
	v_bfe_u32 v8, v35, 16, 1
	v_lshrrev_b32_e32 v3, 16, v3
	v_add3_u32 v8, v35, v8, s3
	v_and_or_b32 v21, v8, s23, v3
	v_or_b32_e32 v3, v17, v16
	v_lshlrev_b32_e32 v208, 11, v3
	v_lshl_add_u64 v[6:7], v[6:7], 0, v[208:209]
	global_store_dwordx4 v[6:7], v[18:21], off sc1
	s_waitcnt lgkmcnt(0)

.LBB0_740:
	s_lshl_b32 s24, s15, 1
	s_lshl_b32 s21, s2, 1
	v_or_b32_e32 v38, s24, v0
	s_add_i32 s26, s24, 4
	v_or_b32_e32 v17, s21, v1
	s_add_i32 s25, s21, 4
	s_add_i32 s27, s21, 8
	s_add_i32 s30, s24, 8
	s_add_i32 s31, s21, 12
	s_add_i32 s36, s21, 16
	s_add_i32 s49, s21, 20
	s_add_i32 s51, s21, 24
	s_add_i32 s21, s21, 28
	v_add_u32_e32 v20, v38, v8
	v_or_b32_e32 v40, s26, v0
	s_add_i32 s33, s24, 12
	v_add_u32_e32 v18, v17, v3
	v_or_b32_e32 v39, s25, v1
	v_or_b32_e32 v41, s27, v1
	v_or_b32_e32 v42, s30, v0
	v_or_b32_e32 v43, s31, v1
	v_or_b32_e32 v45, s36, v1
	v_or_b32_e32 v47, s49, v1
	v_or_b32_e32 v49, s51, v1
	v_or_b32_e32 v51, s21, v1
	v_mul_lo_u32 v208, v20, s9
	v_add_u32_e32 v22, v40, v8
	v_mov_b32_e32 v19, v209
	s_add_i32 s48, s24, 16
	v_or_b32_e32 v44, s33, v0
	v_mul_lo_u32 v18, v18, s9
	v_add_u32_e32 v20, v39, v3
	v_add_u32_e32 v53, v42, v8
	v_add_u32_e32 v24, v41, v3
	v_add_u32_e32 v26, v43, v3
	v_add_u32_e32 v28, v45, v3
	v_add_u32_e32 v30, v47, v3
	v_add_u32_e32 v32, v49, v3
	v_add_u32_e32 v36, v51, v3
	v_lshl_add_u64 v[34:35], v[208:209], 2, v[10:11]
	v_mul_lo_u32 v208, v22, s9
	v_mov_b32_e32 v21, v209
	s_add_i32 s50, s24, 20
	v_or_b32_e32 v46, s48, v0
	v_add_u32_e32 v54, v44, v8
	v_lshl_add_u64 v[18:19], v[18:19], 2, v[10:11]
	v_mul_lo_u32 v20, v20, s9
	v_mul_lo_u32 v22, v24, s9
	v_mul_lo_u32 v24, v26, s9
	v_mul_lo_u32 v26, v28, s9
	v_mul_lo_u32 v28, v30, s9
	v_mul_lo_u32 v30, v32, s9
	v_mul_lo_u32 v32, v36, s9
	v_lshl_add_u64 v[36:37], v[208:209], 2, v[10:11]
	v_mul_lo_u32 v208, v53, s9
	s_add_i32 s56, s24, 24
	v_or_b32_e32 v48, s50, v0
	v_add_u32_e32 v55, v46, v8
	v_lshl_add_u64 v[20:21], v[20:21], 2, v[10:11]
	global_load_dword v53, v[34:35], off offset:2048
	global_load_dword v59, v[18:19], off offset:2048
	global_load_dword v60, v[36:37], off offset:2048
	global_load_dword v61, v[20:21], off offset:2048
	v_lshl_add_u64 v[18:19], v[208:209], 2, v[10:11]
	v_mul_lo_u32 v208, v54, s9
	v_mov_b32_e32 v23, v209
	v_mov_b32_e32 v25, v209
	s_add_i32 s24, s24, 28
	v_or_b32_e32 v50, s56, v0
	v_add_u32_e32 v56, v48, v8
	v_lshl_add_u64 v[20:21], v[208:209], 2, v[10:11]
	v_mul_lo_u32 v208, v55, s9
	v_or_b32_e32 v52, s24, v0
	v_add_u32_e32 v57, v50, v8
	v_lshl_add_u64 v[22:23], v[22:23], 2, v[10:11]
	v_lshl_add_u64 v[24:25], v[24:25], 2, v[10:11]
	global_load_dword v54, v[18:19], off offset:2048
	global_load_dword v55, v[22:23], off offset:2048
	global_load_dword v62, v[20:21], off offset:2048
	global_load_dword v63, v[24:25], off offset:2048
	v_lshl_add_u64 v[18:19], v[208:209], 2, v[10:11]
	v_mul_lo_u32 v208, v56, s9
	v_mov_b32_e32 v27, v209
	v_mov_b32_e32 v29, v209
	v_add_u32_e32 v58, v52, v8
	v_lshl_add_u64 v[20:21], v[208:209], 2, v[10:11]
	v_mul_lo_u32 v208, v57, s9
	v_mov_b32_e32 v31, v209
	v_mov_b32_e32 v33, v209
	v_lshl_add_u64 v[26:27], v[26:27], 2, v[10:11]
	v_lshl_add_u64 v[28:29], v[28:29], 2, v[10:11]
	global_load_dword v56, v[18:19], off offset:2048
	global_load_dword v57, v[26:27], off offset:2048
	global_load_dword v64, v[20:21], off offset:2048
	global_load_dword v65, v[28:29], off offset:2048
	v_lshl_add_u64 v[18:19], v[208:209], 2, v[10:11]
	v_mul_lo_u32 v208, v58, s9
	v_lshl_add_u64 v[30:31], v[30:31], 2, v[10:11]
	v_lshl_add_u64 v[32:33], v[32:33], 2, v[10:11]
	v_lshl_add_u64 v[20:21], v[208:209], 2, v[10:11]
	global_load_dword v58, v[18:19], off offset:2048
	global_load_dword v66, v[30:31], off offset:2048
	global_load_dword v67, v[20:21], off offset:2048
	global_load_dword v68, v[32:33], off offset:2048
	s_add_i32 s15, s15, 16
	s_add_i32 s2, s2, 16
	s_add_i32 s20, s20, -16
	v_mad_u64_u32 v[18:19], s[24:25], v38, s8, v[2:3]
	s_cmp_lg_u32 s20, 0
	v_mad_u64_u32 v[20:21], s[24:25], v17, s8, v[2:3]
	v_mad_u64_u32 v[22:23], s[24:25], v40, s8, v[2:3]
	v_mad_u64_u32 v[24:25], s[24:25], v39, s8, v[2:3]
	v_mad_u64_u32 v[26:27], s[24:25], v42, s8, v[2:3]
	v_mad_u64_u32 v[28:29], s[24:25], v41, s8, v[2:3]
	v_mad_u64_u32 v[30:31], s[24:25], v44, s8, v[2:3]
	v_mad_u64_u32 v[32:33], s[24:25], v43, s8, v[2:3]
	v_mad_u64_u32 v[34:35], s[24:25], v46, s8, v[2:3]
	v_mad_u64_u32 v[36:37], s[24:25], v45, s8, v[2:3]
	v_mad_u64_u32 v[38:39], s[24:25], v48, s8, v[2:3]
	v_mad_u64_u32 v[40:41], s[24:25], v47, s8, v[2:3]
	v_mad_u64_u32 v[42:43], s[24:25], v50, s8, v[2:3]
	v_mad_u64_u32 v[44:45], s[24:25], v49, s8, v[2:3]
	v_mad_u64_u32 v[46:47], s[24:25], v52, s8, v[2:3]
	v_mad_u64_u32 v[48:49], s[24:25], v51, s8, v[2:3]
	s_waitcnt vmcnt(15)
	ds_write_b32 v18, v53
	s_waitcnt vmcnt(14)
	ds_write_b32 v20, v59
	s_waitcnt vmcnt(13)
	ds_write_b32 v22, v60
	s_waitcnt vmcnt(12)
	ds_write_b32 v24, v61
	s_waitcnt vmcnt(11)
	ds_write_b32 v26, v54
	s_waitcnt vmcnt(10)
	ds_write_b32 v28, v55
	s_waitcnt vmcnt(9)
	ds_write_b32 v30, v62
	s_waitcnt vmcnt(8)
	ds_write_b32 v32, v63
	s_waitcnt vmcnt(7)
	ds_write_b32 v34, v56
	s_waitcnt vmcnt(6)
	ds_write_b32 v36, v57
	s_waitcnt vmcnt(5)
	ds_write_b32 v38, v64
	s_waitcnt vmcnt(4)
	ds_write_b32 v40, v65
	s_waitcnt vmcnt(3)
	ds_write_b32 v42, v58
	s_waitcnt vmcnt(2)
	ds_write_b32 v44, v66
	s_waitcnt vmcnt(1)
	ds_write_b32 v46, v67
	s_waitcnt vmcnt(0)
	ds_write_b32 v48, v68
	s_cbranch_scc1 .LBB0_740
	v_mul_hi_i32_i24_e32 v11, 0x600000, v6
	v_mul_i32_i24_e32 v10, 0x600000, v6
	s_waitcnt lgkmcnt(0)
	v_add_u32_e32 v3, 0xfffff100, v7
	v_lshl_add_u64 v[6:7], s[40:41], 0, v[10:11]
	ds_read2_b32 v[10:11], v13 offset1:8
	ds_read2_b32 v[22:23], v13 offset0:33 offset1:41
	ds_read2_b32 v[24:25], v13 offset0:66 offset1:74
	ds_read2_b32 v[26:27], v13 offset0:99 offset1:107
	v_lshlrev_b32_e32 v208, 1, v8
	s_waitcnt lgkmcnt(3)
	v_bfe_u32 v8, v10, 16, 1
	v_add3_u32 v8, v10, v8, s3
	s_waitcnt lgkmcnt(2)
	v_bfe_u32 v10, v22, 16, 1
	ds_read2_b32 v[28:29], v13 offset0:132 offset1:140
	v_lshrrev_b32_e32 v8, 16, v8
	v_add3_u32 v10, v22, v10, s3
	ds_read2_b32 v[30:31], v13 offset0:165 offset1:173
	v_and_or_b32 v18, v10, s23, v8
	s_waitcnt lgkmcnt(3)
	v_bfe_u32 v8, v24, 16, 1
	v_add3_u32 v8, v24, v8, s3
	s_waitcnt lgkmcnt(2)
	v_bfe_u32 v10, v26, 16, 1
	ds_read2_b32 v[32:33], v13 offset0:198 offset1:206
	v_lshrrev_b32_e32 v8, 16, v8
	v_add3_u32 v10, v26, v10, s3
	ds_read2_b32 v[34:35], v13 offset0:231 offset1:239
	v_and_or_b32 v19, v10, s23, v8
	s_waitcnt lgkmcnt(3)
	v_bfe_u32 v8, v28, 16, 1
	v_add3_u32 v8, v28, v8, s3
	s_waitcnt lgkmcnt(2)
	v_bfe_u32 v10, v30, 16, 1
	v_lshrrev_b32_e32 v8, 16, v8
	v_add3_u32 v10, v30, v10, s3
	v_and_or_b32 v20, v10, s23, v8
	s_waitcnt lgkmcnt(1)
	v_bfe_u32 v8, v32, 16, 1
	v_add3_u32 v8, v32, v8, s3
	s_waitcnt lgkmcnt(0)
	v_bfe_u32 v10, v34, 16, 1
	v_lshl_add_u64 v[6:7], v[6:7], 0, v[208:209]
	v_lshlrev_b32_e32 v208, 1, v4
	v_lshrrev_b32_e32 v8, 16, v8
	v_add3_u32 v10, v34, v10, s3
	v_lshl_add_u64 v[6:7], v[6:7], 0, v[208:209]
	v_and_or_b32 v21, v10, s23, v8
	v_or_b32_e32 v208, v3, v12
	v_bfe_u32 v8, v11, 16, 1
	v_lshlrev_b64 v[36:37], 11, v[208:209]
	v_add3_u32 v8, v11, v8, s3
	v_bfe_u32 v10, v23, 16, 1
	v_lshl_add_u64 v[36:37], v[6:7], 0, v[36:37]
	v_lshrrev_b32_e32 v8, 16, v8
	v_add3_u32 v10, v23, v10, s3
	global_store_dwordx4 v[36:37], v[18:21], off sc1
	v_or_b32_e32 v208, v3, v14
	v_lshlrev_b64 v[22:23], 11, v[208:209]
	v_and_or_b32 v18, v10, s23, v8
	v_bfe_u32 v8, v25, 16, 1
	v_add3_u32 v8, v25, v8, s3
	v_bfe_u32 v10, v27, 16, 1
	v_lshrrev_b32_e32 v8, 16, v8
	v_add3_u32 v10, v27, v10, s3
	v_and_or_b32 v19, v10, s23, v8
	v_bfe_u32 v8, v29, 16, 1
	v_add3_u32 v8, v29, v8, s3
	v_bfe_u32 v10, v31, 16, 1
	v_lshrrev_b32_e32 v8, 16, v8
	v_add3_u32 v10, v31, v10, s3
	v_and_or_b32 v20, v10, s23, v8
	v_bfe_u32 v8, v33, 16, 1
	v_add3_u32 v8, v33, v8, s3
	v_bfe_u32 v10, v35, 16, 1
	v_lshrrev_b32_e32 v8, 16, v8
	v_add3_u32 v10, v35, v10, s3
	v_and_or_b32 v21, v10, s23, v8
	ds_read2_b32 v[10:11], v13 offset0:16 offset1:24
	v_lshl_add_u64 v[22:23], v[6:7], 0, v[22:23]
	global_store_dwordx4 v[22:23], v[18:21], off sc1
	ds_read2_b32 v[22:23], v13 offset0:49 offset1:57
	ds_read2_b32 v[24:25], v13 offset0:82 offset1:90
	ds_read2_b32 v[26:27], v13 offset0:115 offset1:123
	s_waitcnt lgkmcnt(3)
	v_bfe_u32 v8, v10, 16, 1
	v_add3_u32 v8, v10, v8, s3
	s_waitcnt lgkmcnt(2)
	v_bfe_u32 v10, v22, 16, 1
	ds_read2_b32 v[28:29], v13 offset0:148 offset1:156
	v_lshrrev_b32_e32 v8, 16, v8
	v_add3_u32 v10, v22, v10, s3
	ds_read2_b32 v[30:31], v13 offset0:181 offset1:189
	v_and_or_b32 v18, v10, s23, v8
	s_waitcnt lgkmcnt(3)
	v_bfe_u32 v8, v24, 16, 1
	v_add3_u32 v8, v24, v8, s3
	s_waitcnt lgkmcnt(2)
	v_bfe_u32 v10, v26, 16, 1
	ds_read2_b32 v[32:33], v13 offset0:214 offset1:222
	v_lshrrev_b32_e32 v8, 16, v8
	v_add3_u32 v10, v26, v10, s3
	ds_read2_b32 v[34:35], v13 offset0:247 offset1:255
	v_and_or_b32 v19, v10, s23, v8
	s_waitcnt lgkmcnt(3)
	v_bfe_u32 v8, v28, 16, 1
	v_add3_u32 v8, v28, v8, s3
	s_waitcnt lgkmcnt(2)
	v_bfe_u32 v10, v30, 16, 1
	v_lshrrev_b32_e32 v8, 16, v8
	v_add3_u32 v10, v30, v10, s3
	v_and_or_b32 v20, v10, s23, v8
	s_waitcnt lgkmcnt(1)
	v_bfe_u32 v8, v32, 16, 1
	v_add3_u32 v8, v32, v8, s3
	s_waitcnt lgkmcnt(0)
	v_bfe_u32 v10, v34, 16, 1
	v_lshrrev_b32_e32 v8, 16, v8
	v_add3_u32 v10, v34, v10, s3
	v_and_or_b32 v21, v10, s23, v8
	v_or_b32_e32 v208, v3, v15
	v_bfe_u32 v8, v11, 16, 1
	v_lshlrev_b64 v[36:37], 11, v[208:209]
	v_add3_u32 v8, v11, v8, s3
	v_bfe_u32 v10, v23, 16, 1
	v_lshl_add_u64 v[36:37], v[6:7], 0, v[36:37]
	v_lshrrev_b32_e32 v8, 16, v8
	v_add3_u32 v10, v23, v10, s3
	global_store_dwordx4 v[36:37], v[18:21], off sc1
	v_or_b32_e32 v208, v3, v16
	s_mov_b32 s33, 0x9000
	v_and_or_b32 v18, v10, s23, v8
	v_bfe_u32 v8, v25, 16, 1
	v_add3_u32 v8, v25, v8, s3
	v_bfe_u32 v10, v27, 16, 1
	v_lshrrev_b32_e32 v8, 16, v8
	v_add3_u32 v10, v27, v10, s3
	v_and_or_b32 v19, v10, s23, v8
	v_bfe_u32 v8, v29, 16, 1
	v_add3_u32 v8, v29, v8, s3
	v_bfe_u32 v10, v31, 16, 1
	v_lshrrev_b32_e32 v8, 16, v8
	v_add3_u32 v10, v31, v10, s3
	v_and_or_b32 v20, v10, s23, v8
	v_bfe_u32 v8, v33, 16, 1
	v_add3_u32 v8, v33, v8, s3
	v_bfe_u32 v10, v35, 16, 1
	v_lshrrev_b32_e32 v8, 16, v8
	v_add3_u32 v10, v35, v10, s3
	v_and_or_b32 v21, v10, s23, v8
	v_lshlrev_b64 v[10:11], 11, v[208:209]
	v_lshl_add_u64 v[6:7], v[6:7], 0, v[10:11]
	global_store_dwordx4 v[6:7], v[18:21], off sc1
	s_waitcnt lgkmcnt(0)

.LBB0_751:
	s_lshl_b32 s24, s15, 1
	s_lshl_b32 s21, s2, 1
	v_or_b32_e32 v38, s24, v0
	s_add_i32 s26, s24, 4
	v_or_b32_e32 v17, s21, v1
	s_add_i32 s25, s21, 4
	s_add_i32 s27, s21, 8
	s_add_i32 s30, s24, 8
	s_add_i32 s31, s21, 12
	s_add_i32 s36, s21, 16
	s_add_i32 s47, s21, 20
	s_add_i32 s49, s21, 24
	s_add_i32 s21, s21, 28
	v_add_u32_e32 v20, v38, v8
	v_or_b32_e32 v40, s26, v0
	s_add_i32 s33, s24, 12
	v_add_u32_e32 v18, v17, v3
	v_or_b32_e32 v39, s25, v1
	v_or_b32_e32 v41, s27, v1
	v_or_b32_e32 v42, s30, v0
	v_or_b32_e32 v43, s31, v1
	v_or_b32_e32 v45, s36, v1
	v_or_b32_e32 v47, s47, v1
	v_or_b32_e32 v49, s49, v1
	v_or_b32_e32 v51, s21, v1
	v_mul_lo_u32 v208, v20, s9
	v_add_u32_e32 v22, v40, v8
	v_mov_b32_e32 v19, v209
	s_add_i32 s46, s24, 16
	v_or_b32_e32 v44, s33, v0
	v_mul_lo_u32 v18, v18, s9
	v_add_u32_e32 v20, v39, v3
	v_add_u32_e32 v53, v42, v8
	v_add_u32_e32 v24, v41, v3
	v_add_u32_e32 v26, v43, v3
	v_add_u32_e32 v28, v45, v3
	v_add_u32_e32 v30, v47, v3
	v_add_u32_e32 v32, v49, v3
	v_add_u32_e32 v36, v51, v3
	v_lshl_add_u64 v[34:35], v[208:209], 2, v[10:11]
	v_mul_lo_u32 v208, v22, s9
	v_mov_b32_e32 v21, v209
	s_add_i32 s48, s24, 20
	v_or_b32_e32 v46, s46, v0
	v_add_u32_e32 v54, v44, v8
	v_lshl_add_u64 v[18:19], v[18:19], 2, v[10:11]
	v_mul_lo_u32 v20, v20, s9
	v_mul_lo_u32 v22, v24, s9
	v_mul_lo_u32 v24, v26, s9
	v_mul_lo_u32 v26, v28, s9
	v_mul_lo_u32 v28, v30, s9
	v_mul_lo_u32 v30, v32, s9
	v_mul_lo_u32 v32, v36, s9
	v_lshl_add_u64 v[36:37], v[208:209], 2, v[10:11]
	v_mul_lo_u32 v208, v53, s9
	s_add_i32 s50, s24, 24
	v_or_b32_e32 v48, s48, v0
	v_add_u32_e32 v55, v46, v8
	v_lshl_add_u64 v[20:21], v[20:21], 2, v[10:11]
	global_load_dword v53, v[34:35], off
	global_load_dword v59, v[18:19], off
	global_load_dword v60, v[36:37], off
	global_load_dword v61, v[20:21], off
	v_lshl_add_u64 v[18:19], v[208:209], 2, v[10:11]
	v_mul_lo_u32 v208, v54, s9
	v_mov_b32_e32 v23, v209
	v_mov_b32_e32 v25, v209
	s_add_i32 s24, s24, 28
	v_or_b32_e32 v50, s50, v0
	v_add_u32_e32 v56, v48, v8
	v_lshl_add_u64 v[20:21], v[208:209], 2, v[10:11]
	v_mul_lo_u32 v208, v55, s9
	v_or_b32_e32 v52, s24, v0
	v_add_u32_e32 v57, v50, v8
	v_lshl_add_u64 v[22:23], v[22:23], 2, v[10:11]
	v_lshl_add_u64 v[24:25], v[24:25], 2, v[10:11]
	global_load_dword v54, v[18:19], off
	global_load_dword v55, v[22:23], off
	global_load_dword v62, v[20:21], off
	global_load_dword v63, v[24:25], off
	v_lshl_add_u64 v[18:19], v[208:209], 2, v[10:11]
	v_mul_lo_u32 v208, v56, s9
	v_mov_b32_e32 v27, v209
	v_mov_b32_e32 v29, v209
	v_add_u32_e32 v58, v52, v8
	v_lshl_add_u64 v[20:21], v[208:209], 2, v[10:11]
	v_mul_lo_u32 v208, v57, s9
	v_mov_b32_e32 v31, v209
	v_mov_b32_e32 v33, v209
	v_lshl_add_u64 v[26:27], v[26:27], 2, v[10:11]
	v_lshl_add_u64 v[28:29], v[28:29], 2, v[10:11]
	global_load_dword v56, v[18:19], off
	global_load_dword v57, v[26:27], off
	global_load_dword v64, v[20:21], off
	global_load_dword v65, v[28:29], off
	v_lshl_add_u64 v[18:19], v[208:209], 2, v[10:11]
	v_mul_lo_u32 v208, v58, s9
	v_lshl_add_u64 v[30:31], v[30:31], 2, v[10:11]
	v_lshl_add_u64 v[32:33], v[32:33], 2, v[10:11]
	v_lshl_add_u64 v[20:21], v[208:209], 2, v[10:11]
	global_load_dword v58, v[18:19], off
	global_load_dword v66, v[30:31], off
	global_load_dword v67, v[20:21], off
	global_load_dword v68, v[32:33], off
	s_add_i32 s15, s15, 16
	s_add_i32 s2, s2, 16
	s_add_i32 s20, s20, -16
	v_mad_u64_u32 v[18:19], s[24:25], v38, s8, v[2:3]
	s_cmp_lg_u32 s20, 0
	v_mad_u64_u32 v[20:21], s[24:25], v17, s8, v[2:3]
	v_mad_u64_u32 v[22:23], s[24:25], v40, s8, v[2:3]
	v_mad_u64_u32 v[24:25], s[24:25], v39, s8, v[2:3]
	v_mad_u64_u32 v[26:27], s[24:25], v42, s8, v[2:3]
	v_mad_u64_u32 v[28:29], s[24:25], v41, s8, v[2:3]
	v_mad_u64_u32 v[30:31], s[24:25], v44, s8, v[2:3]
	v_mad_u64_u32 v[32:33], s[24:25], v43, s8, v[2:3]
	v_mad_u64_u32 v[34:35], s[24:25], v46, s8, v[2:3]
	v_mad_u64_u32 v[36:37], s[24:25], v45, s8, v[2:3]
	v_mad_u64_u32 v[38:39], s[24:25], v48, s8, v[2:3]
	v_mad_u64_u32 v[40:41], s[24:25], v47, s8, v[2:3]
	v_mad_u64_u32 v[42:43], s[24:25], v50, s8, v[2:3]
	v_mad_u64_u32 v[44:45], s[24:25], v49, s8, v[2:3]
	v_mad_u64_u32 v[46:47], s[24:25], v52, s8, v[2:3]
	v_mad_u64_u32 v[48:49], s[24:25], v51, s8, v[2:3]
	s_waitcnt vmcnt(15)
	ds_write_b32 v18, v53
	s_waitcnt vmcnt(14)
	ds_write_b32 v20, v59
	s_waitcnt vmcnt(13)
	ds_write_b32 v22, v60
	s_waitcnt vmcnt(12)
	ds_write_b32 v24, v61
	s_waitcnt vmcnt(11)
	ds_write_b32 v26, v54
	s_waitcnt vmcnt(10)
	ds_write_b32 v28, v55
	s_waitcnt vmcnt(9)
	ds_write_b32 v30, v62
	s_waitcnt vmcnt(8)
	ds_write_b32 v32, v63
	s_waitcnt vmcnt(7)
	ds_write_b32 v34, v56
	s_waitcnt vmcnt(6)
	ds_write_b32 v36, v57
	s_waitcnt vmcnt(5)
	ds_write_b32 v38, v64
	s_waitcnt vmcnt(4)
	ds_write_b32 v40, v65
	s_waitcnt vmcnt(3)
	ds_write_b32 v42, v58
	s_waitcnt vmcnt(2)
	ds_write_b32 v44, v66
	s_waitcnt vmcnt(1)
	ds_write_b32 v46, v67
	s_waitcnt vmcnt(0)
	ds_write_b32 v48, v68
	s_cbranch_scc1 .LBB0_751
	s_waitcnt lgkmcnt(0)
	ds_read2_b32 v[22:23], v13 offset1:8
	ds_read2_b32 v[24:25], v13 offset0:33 offset1:41
	ds_read2_b32 v[26:27], v13 offset0:66 offset1:74
	ds_read2_b32 v[28:29], v13 offset0:99 offset1:107
	v_mov_b64_e32 v[10:11], s[42:43]
	s_mov_b32 s2, 0x980000
	s_waitcnt lgkmcnt(3)
	v_bfe_u32 v3, v22, 16, 1
	v_mad_i64_i32 v[10:11], s[20:21], v6, s2, v[10:11]
	v_add3_u32 v3, v22, v3, s3
	s_waitcnt lgkmcnt(2)
	v_bfe_u32 v6, v24, 16, 1
	ds_read2_b32 v[30:31], v13 offset0:132 offset1:140
	v_lshrrev_b32_e32 v3, 16, v3
	v_add3_u32 v6, v24, v6, s3
	ds_read2_b32 v[32:33], v13 offset0:165 offset1:173
	v_and_or_b32 v18, v6, s23, v3
	s_waitcnt lgkmcnt(3)
	v_bfe_u32 v3, v26, 16, 1
	v_add3_u32 v3, v26, v3, s3
	s_waitcnt lgkmcnt(2)
	v_bfe_u32 v6, v28, 16, 1
	ds_read2_b32 v[34:35], v13 offset0:198 offset1:206
	v_lshrrev_b32_e32 v3, 16, v3
	v_add3_u32 v6, v28, v6, s3
	ds_read2_b32 v[36:37], v13 offset0:231 offset1:239
	v_and_or_b32 v19, v6, s23, v3
	s_waitcnt lgkmcnt(3)
	v_bfe_u32 v3, v30, 16, 1
	v_add3_u32 v3, v30, v3, s3
	s_waitcnt lgkmcnt(2)
	v_bfe_u32 v6, v32, 16, 1
	v_lshrrev_b32_e32 v3, 16, v3
	v_add3_u32 v6, v32, v6, s3
	v_and_or_b32 v20, v6, s23, v3
	s_waitcnt lgkmcnt(1)
	v_bfe_u32 v3, v34, 16, 1
	v_add3_u32 v3, v34, v3, s3
	s_waitcnt lgkmcnt(0)
	v_bfe_u32 v6, v36, 16, 1
	v_lshlrev_b32_e32 v208, 1, v8
	v_lshrrev_b32_e32 v3, 16, v3
	v_add3_u32 v6, v36, v6, s3
	v_or_b32_e32 v38, v7, v12
	v_lshl_add_u64 v[10:11], v[10:11], 0, v[208:209]
	v_lshlrev_b32_e32 v208, 1, v4
	v_and_or_b32 v21, v6, s23, v3
	v_ashrrev_i32_e32 v39, 31, v38
	v_bfe_u32 v3, v23, 16, 1
	v_lshl_add_u64 v[10:11], v[10:11], 0, v[208:209]
	v_lshlrev_b64 v[38:39], 11, v[38:39]
	v_add3_u32 v3, v23, v3, s3
	v_bfe_u32 v6, v25, 16, 1
	v_lshl_add_u64 v[38:39], v[10:11], 0, v[38:39]
	v_lshrrev_b32_e32 v3, 16, v3
	v_add3_u32 v6, v25, v6, s3
	global_store_dwordx4 v[38:39], v[18:21], off sc1
	v_or_b32_e32 v22, v7, v14
	v_ashrrev_i32_e32 v23, 31, v22
	v_and_or_b32 v18, v6, s23, v3
	v_bfe_u32 v3, v27, 16, 1
	v_add3_u32 v3, v27, v3, s3
	v_bfe_u32 v6, v29, 16, 1
	v_lshrrev_b32_e32 v3, 16, v3
	v_add3_u32 v6, v29, v6, s3
	v_and_or_b32 v19, v6, s23, v3
	v_bfe_u32 v3, v31, 16, 1
	v_add3_u32 v3, v31, v3, s3
	v_bfe_u32 v6, v33, 16, 1
	v_lshrrev_b32_e32 v3, 16, v3
	v_add3_u32 v6, v33, v6, s3
	v_and_or_b32 v20, v6, s23, v3
	v_bfe_u32 v3, v35, 16, 1
	v_add3_u32 v3, v35, v3, s3
	v_bfe_u32 v6, v37, 16, 1
	v_lshrrev_b32_e32 v3, 16, v3
	v_add3_u32 v6, v37, v6, s3
	v_lshlrev_b64 v[22:23], 11, v[22:23]
	v_and_or_b32 v21, v6, s23, v3
	ds_read2_b32 v[24:25], v13 offset0:16 offset1:24
	v_lshl_add_u64 v[22:23], v[10:11], 0, v[22:23]
	global_store_dwordx4 v[22:23], v[18:21], off sc1
	ds_read2_b32 v[22:23], v13 offset0:49 offset1:57
	ds_read2_b32 v[26:27], v13 offset0:82 offset1:90
	ds_read2_b32 v[28:29], v13 offset0:115 offset1:123
	s_waitcnt lgkmcnt(3)
	v_bfe_u32 v3, v24, 16, 1
	v_add3_u32 v3, v24, v3, s3
	s_waitcnt lgkmcnt(2)
	v_bfe_u32 v6, v22, 16, 1
	ds_read2_b32 v[30:31], v13 offset0:148 offset1:156
	v_lshrrev_b32_e32 v3, 16, v3
	v_add3_u32 v6, v22, v6, s3
	ds_read2_b32 v[32:33], v13 offset0:181 offset1:189
	v_and_or_b32 v18, v6, s23, v3
	s_waitcnt lgkmcnt(3)
	v_bfe_u32 v3, v26, 16, 1
	v_add3_u32 v3, v26, v3, s3
	s_waitcnt lgkmcnt(2)
	v_bfe_u32 v6, v28, 16, 1
	ds_read2_b32 v[34:35], v13 offset0:214 offset1:222
	v_lshrrev_b32_e32 v3, 16, v3
	v_add3_u32 v6, v28, v6, s3
	ds_read2_b32 v[36:37], v13 offset0:247 offset1:255
	v_and_or_b32 v19, v6, s23, v3
	s_waitcnt lgkmcnt(3)
	v_bfe_u32 v3, v30, 16, 1
	v_add3_u32 v3, v30, v3, s3
	s_waitcnt lgkmcnt(2)
	v_bfe_u32 v6, v32, 16, 1
	v_lshrrev_b32_e32 v3, 16, v3
	v_add3_u32 v6, v32, v6, s3
	v_and_or_b32 v20, v6, s23, v3
	s_waitcnt lgkmcnt(1)
	v_bfe_u32 v3, v34, 16, 1
	v_add3_u32 v3, v34, v3, s3
	s_waitcnt lgkmcnt(0)
	v_bfe_u32 v6, v36, 16, 1
	v_lshrrev_b32_e32 v3, 16, v3
	v_add3_u32 v6, v36, v6, s3
	v_or_b32_e32 v38, v7, v15
	v_and_or_b32 v21, v6, s23, v3
	v_ashrrev_i32_e32 v39, 31, v38
	v_bfe_u32 v3, v25, 16, 1
	v_lshlrev_b64 v[38:39], 11, v[38:39]
	v_add3_u32 v3, v25, v3, s3
	v_bfe_u32 v6, v23, 16, 1
	v_lshl_add_u64 v[38:39], v[10:11], 0, v[38:39]
	v_lshrrev_b32_e32 v3, 16, v3
	v_add3_u32 v6, v23, v6, s3
	global_store_dwordx4 v[38:39], v[18:21], off sc1
	s_mov_b32 s33, 0x9000
	s_nop 0
	v_and_or_b32 v18, v6, s23, v3
	v_bfe_u32 v3, v27, 16, 1
	v_add3_u32 v3, v27, v3, s3
	v_bfe_u32 v6, v29, 16, 1
	v_lshrrev_b32_e32 v3, 16, v3
	v_add3_u32 v6, v29, v6, s3
	v_and_or_b32 v19, v6, s23, v3
	v_bfe_u32 v3, v31, 16, 1
	v_add3_u32 v3, v31, v3, s3
	v_bfe_u32 v6, v33, 16, 1
	v_lshrrev_b32_e32 v3, 16, v3
	v_add3_u32 v6, v33, v6, s3
	v_and_or_b32 v20, v6, s23, v3
	v_bfe_u32 v3, v35, 16, 1
	v_add3_u32 v3, v35, v3, s3
	v_bfe_u32 v6, v37, 16, 1
	v_lshrrev_b32_e32 v3, 16, v3
	v_add3_u32 v6, v37, v6, s3
	v_and_or_b32 v21, v6, s23, v3
	v_or_b32_e32 v6, v7, v16
	v_ashrrev_i32_e32 v7, 31, v6
	v_lshlrev_b64 v[6:7], 11, v[6:7]
	v_lshl_add_u64 v[6:7], v[10:11], 0, v[6:7]
	global_store_dwordx4 v[6:7], v[18:21], off sc1
	s_waitcnt lgkmcnt(0)
	s_branch .LBB0_726
